# gemm_out big items (w_o, ffn_down, branch): decode swaps jq bits 2,5 so the two WGs of a CU share the 256-row A tile instead of the B tile
# baseline (speedup 1.0000x reference)
.LBB0_123:
	s_and_b64 vcc, exec, s[10:11]
	s_cbranch_vccz .LBB0_118
	s_lshr_b32 s10, s12, 5
	s_lshr_b32 s2, s12, 8
	s_xor_b32 s10, s10, s2
	s_and_b32 s10, s10, 1
	s_mulk_i32 s10, 0x120
	s_xor_b32 s24, s12, s10
	s_lshr_b32 s10, s24, 3
	s_and_b32 s2, s23, 7
	s_and_b32 s10, s10, 0xfffff8
	v_mov_b32_e32 v22, v196
	s_or_b32 s2, s10, s2
	s_lshl_b32 s10, s2, 8
	v_lshrrev_b32_e32 v0, 2, v22
	s_lshl_b32 s11, s24, 4
	v_and_b32_e32 v0, 12, v0
	s_and_b32 s24, s11, 0x380
	s_ashr_i32 s11, s10, 31
	s_mul_i32 s2, s2, 0x160000
	v_lshrrev_b32_e64 v24, v0, s57
	s_mul_hi_i32 s13, s10, 0x1600
	s_add_u32 s12, s15, s2
	v_xor_b32_e32 v0, v24, v22
	s_addc_u32 s13, s16, s13
	s_mul_i32 s2, s24, 0x1600
	v_lshlrev_b32_e32 v0, 4, v0
	s_add_u32 s26, s17, s2
	v_ashrrev_i32_e32 v23, 2, v22
	v_and_b32_e32 v0, 48, v0
	s_addc_u32 s27, s18, 0
	v_lshl_add_u64 v[2:3], s[12:13], 0, v[0:1]
	v_add_u32_e32 v12, 64, v23
	v_add_u32_e32 v8, 0x80, v23
	v_add_u32_e32 v10, 0xc0, v23
	v_mad_i64_i32 v[4:5], s[12:13], v23, s29, v[2:3]
	v_mad_i64_i32 v[6:7], s[12:13], v12, s29, v[2:3]
	v_mad_i64_i32 v[8:9], s[12:13], v8, s29, v[2:3]
	v_mad_i64_i32 v[2:3], s[12:13], v10, s29, v[2:3]
	v_mov_b64_e32 v[10:11], s[26:27]
	v_mad_i64_i32 v[12:13], s[12:13], v12, s29, v[10:11]
	v_lshl_add_u32 v156, v22, 4, 0
	v_add_u32_e32 v16, 0x1000, v156
	v_readfirstlane_b32 s12, v156
	v_and_b32_e32 v15, 12, v22
	s_mov_b32 m0, s12
	v_readfirstlane_b32 s12, v16
	v_add_u32_e32 v18, 0x2000, v156
	v_lshrrev_b32_e32 v14, 4, v22
	v_lshrrev_b32_e64 v15, v15, s57
	global_load_lds_dwordx4 v[4:5], off
	s_mov_b32 m0, s12
	v_readfirstlane_b32 s12, v18
	v_add_u32_e32 v20, 0x3000, v156
	v_xor_b32_e32 v14, v15, v14
	global_load_lds_dwordx4 v[6:7], off
	s_mov_b32 m0, s12
	v_readfirstlane_b32 s12, v20
	v_lshlrev_b32_e32 v26, 4, v14
	global_load_lds_dwordx4 v[8:9], off
	s_mov_b32 m0, s12
	v_mad_i64_i32 v[10:11], s[12:13], v23, s29, v[10:11]
	v_lshl_add_u64 v[10:11], v[10:11], 0, v[0:1]
	v_lshl_add_u64 v[12:13], v[12:13], 0, v[0:1]
	v_and_b32_e32 v0, 48, v26
	v_add_u32_e32 v26, 0x4000, v156
	global_load_lds_dwordx4 v[2:3], off
	v_readfirstlane_b32 s12, v26
	v_add_u32_e32 v26, 0x5000, v156
	s_mov_b32 m0, s12
	v_readfirstlane_b32 s12, v26
	v_add_u32_e32 v26, 0x6000, v156
	global_load_lds_dwordx4 v[10:11], off
	s_mov_b32 m0, s12
	v_readfirstlane_b32 s12, v26
	v_lshl_add_u64 v[14:15], v[4:5], 0, 64
	global_load_lds_dwordx4 v[12:13], off
	s_mov_b32 m0, s12
	v_lshl_add_u64 v[16:17], v[6:7], 0, 64
	global_load_lds_dwordx4 v[14:15], off
	v_add_u32_e32 v14, 0x7000, v156
	v_lshl_add_u64 v[18:19], v[8:9], 0, 64
	v_readfirstlane_b32 s12, v14
	v_add_u32_e32 v14, 0x8000, v156
	s_mov_b32 m0, s12
	v_readfirstlane_b32 s12, v14
	v_add_u32_e32 v14, 0x9000, v156
	global_load_lds_dwordx4 v[16:17], off
	s_mov_b32 m0, s12
	v_readfirstlane_b32 s12, v14
	v_add_u32_e32 v14, 0xa000, v156
	v_lshl_add_u64 v[20:21], v[2:3], 0, 64
	global_load_lds_dwordx4 v[18:19], off
	s_mov_b32 m0, s12
	v_readfirstlane_b32 s12, v14
	v_lshl_add_u64 v[10:11], v[10:11], 0, 64
	global_load_lds_dwordx4 v[20:21], off
	s_mov_b32 m0, s12
	v_lshl_add_u64 v[12:13], v[12:13], 0, 64
	global_load_lds_dwordx4 v[10:11], off
	v_add_u32_e32 v10, 0xb000, v156
	v_lshl_add_u64 v[146:147], v[2:3], 0, s[78:79]
	v_readfirstlane_b32 s12, v10
	s_mov_b32 m0, s12
	v_mov_b64_e32 v[2:3], s[2:3]
	global_load_lds_dwordx4 v[12:13], off
	v_lshl_add_u64 v[148:149], v[4:5], 0, s[78:79]
	v_mad_i64_i32 v[2:3], s[12:13], v23, s29, v[2:3]
	v_bitop3_b32 v4, v24, 3, v22 bitop3:0x48
	v_lshl_or_b32 v2, v4, 4, v2
	v_lshlrev_b32_e32 v25, 6, v22
	v_lshl_add_u64 v[154:155], s[0:1], 0, v[2:3]
	v_mov_b32_e32 v2, 0
	s_mov_b32 s25, 2
	v_and_b32_e32 v157, 0x13c0, v25
	v_and_b32_e32 v158, 0xffffe3c0, v25
	v_lshl_add_u64 v[150:151], v[6:7], 0, s[78:79]
	v_lshl_add_u64 v[152:153], v[8:9], 0, s[78:79]
	s_mov_b32 s2, 0
	s_mov_b64 s[12:13], 0
	v_mov_b32_e32 v3, v2
	v_mov_b32_e32 v4, v2
	v_mov_b32_e32 v5, v2
	v_mov_b32_e32 v6, v2
	v_mov_b32_e32 v7, v2
	v_mov_b32_e32 v8, v2
	v_mov_b32_e32 v9, v2
	v_mov_b32_e32 v10, v2
	v_mov_b32_e32 v11, v2
	v_mov_b32_e32 v12, v2
	v_mov_b32_e32 v13, v2
	v_mov_b32_e32 v14, v2
	v_mov_b32_e32 v15, v2
	v_mov_b32_e32 v16, v2
	v_mov_b32_e32 v17, v2
	v_mov_b32_e32 v18, v2
	v_mov_b32_e32 v19, v2
	v_mov_b32_e32 v20, v2
	v_mov_b32_e32 v21, v2
	v_mov_b32_e32 v22, v2
	v_mov_b32_e32 v23, v2
	v_mov_b32_e32 v24, v2
	v_mov_b32_e32 v25, v2
	v_mov_b32_e32 v26, v2
	v_mov_b32_e32 v27, v2
	v_mov_b32_e32 v28, v2
	v_mov_b32_e32 v29, v2
	v_mov_b32_e32 v30, v2
	v_mov_b32_e32 v31, v2
	v_mov_b32_e32 v32, v2
	v_mov_b32_e32 v33, v2
	v_mov_b32_e32 v34, v2
	v_mov_b32_e32 v35, v2
	v_mov_b32_e32 v36, v2
	v_mov_b32_e32 v37, v2
	v_mov_b32_e32 v38, v2
	v_mov_b32_e32 v39, v2
	v_mov_b32_e32 v40, v2
	v_mov_b32_e32 v41, v2
	v_mov_b32_e32 v42, v2
	v_mov_b32_e32 v43, v2
	v_mov_b32_e32 v44, v2
	v_mov_b32_e32 v45, v2
	v_mov_b32_e32 v46, v2
	v_mov_b32_e32 v47, v2
	v_mov_b32_e32 v48, v2
	v_mov_b32_e32 v49, v2
	v_mov_b32_e32 v50, v2
	v_mov_b32_e32 v51, v2
	v_mov_b32_e32 v52, v2
	v_mov_b32_e32 v53, v2
	v_mov_b32_e32 v54, v2
	v_mov_b32_e32 v55, v2
	v_mov_b32_e32 v56, v2
	v_mov_b32_e32 v57, v2
	v_mov_b32_e32 v58, v2
	v_mov_b32_e32 v59, v2
	v_mov_b32_e32 v60, v2
	v_mov_b32_e32 v61, v2
	v_mov_b32_e32 v62, v2
	v_mov_b32_e32 v63, v2
	v_mov_b32_e32 v64, v2
	v_mov_b32_e32 v65, v2
	v_mov_b32_e32 v66, v2
	v_mov_b32_e32 v67, v2
	v_mov_b32_e32 v68, v2
	v_mov_b32_e32 v69, v2
	v_mov_b32_e32 v70, v2
	v_mov_b32_e32 v71, v2
	v_mov_b32_e32 v72, v2
	v_mov_b32_e32 v73, v2
	v_mov_b32_e32 v74, v2
	v_mov_b32_e32 v75, v2
	v_mov_b32_e32 v76, v2
	v_mov_b32_e32 v77, v2
	v_mov_b32_e32 v78, v2
	v_mov_b32_e32 v79, v2
	v_mov_b32_e32 v80, v2
	v_mov_b32_e32 v81, v2
	v_mov_b32_e32 v82, v2
	v_mov_b32_e32 v83, v2
	v_mov_b32_e32 v84, v2
	v_mov_b32_e32 v85, v2
	v_mov_b32_e32 v86, v2
	v_mov_b32_e32 v87, v2
	v_mov_b32_e32 v88, v2
	v_mov_b32_e32 v89, v2
	v_mov_b32_e32 v90, v2
	v_mov_b32_e32 v91, v2
	v_mov_b32_e32 v92, v2
	v_mov_b32_e32 v93, v2
	v_mov_b32_e32 v94, v2
	v_mov_b32_e32 v95, v2
	v_mov_b32_e32 v96, v2
	v_mov_b32_e32 v97, v2
	v_mov_b32_e32 v98, v2
	v_mov_b32_e32 v99, v2
	v_mov_b32_e32 v100, v2
	v_mov_b32_e32 v101, v2
	v_mov_b32_e32 v102, v2
	v_mov_b32_e32 v103, v2
	v_mov_b32_e32 v104, v2
	v_mov_b32_e32 v105, v2
	v_mov_b32_e32 v106, v2
	v_mov_b32_e32 v107, v2
	v_mov_b32_e32 v108, v2
	v_mov_b32_e32 v109, v2
	v_mov_b32_e32 v110, v2
	v_mov_b32_e32 v111, v2
	v_mov_b32_e32 v112, v2
	v_mov_b32_e32 v113, v2
	v_mov_b32_e32 v114, v2
	v_mov_b32_e32 v115, v2
	v_mov_b32_e32 v116, v2
	v_mov_b32_e32 v117, v2
	v_mov_b32_e32 v118, v2
	v_mov_b32_e32 v119, v2
	v_mov_b32_e32 v120, v2
	v_mov_b32_e32 v121, v2
	v_mov_b32_e32 v122, v2
	v_mov_b32_e32 v123, v2
	v_mov_b32_e32 v124, v2
	v_mov_b32_e32 v125, v2
	v_mov_b32_e32 v126, v2
	v_mov_b32_e32 v127, v2
	v_mov_b32_e32 v128, v2
	v_mov_b32_e32 v129, v2

.LBB0_177:
	s_and_b64 vcc, exec, s[10:11]
	s_cbranch_vccz .LBB0_172
	s_lshr_b32 s10, s24, 5
	s_lshr_b32 s2, s24, 8
	s_xor_b32 s10, s10, s2
	s_and_b32 s10, s10, 1
	s_mulk_i32 s10, 0x120
	s_xor_b32 s24, s24, s10
	s_lshr_b32 s10, s24, 3
	s_and_b32 s2, s23, 7
	s_and_b32 s10, s10, 0xfffff8
	v_mov_b32_e32 v20, v196
	s_or_b32 s2, s10, s2
	s_lshl_b32 s10, s2, 8
	v_lshrrev_b32_e32 v0, 2, v20
	v_and_b32_e32 v0, 12, v0
	s_lshl_b32 s2, s24, 4
	s_ashr_i32 s11, s10, 31
	v_lshrrev_b32_e64 v21, v0, s57
	s_and_b32 s24, s2, 0x380
	s_lshl_b64 s[10:11], s[10:11], 11
	v_ashrrev_i32_e32 v2, 2, v20
	v_xor_b32_e32 v0, v21, v20
	s_add_u32 s12, s15, s10
	v_lshlrev_b32_e32 v0, 4, v0
	v_ashrrev_i32_e32 v3, 31, v2
	s_addc_u32 s13, s16, s11
	v_and_b32_e32 v0, 48, v0
	v_lshlrev_b64 v[2:3], 11, v[2:3]
	v_lshl_add_u64 v[4:5], s[12:13], 0, v[0:1]
	v_lshl_add_u64 v[6:7], v[2:3], 0, s[76:77]
	v_lshl_add_u64 v[8:9], v[4:5], 0, v[6:7]
	v_lshl_add_u64 v[4:5], v[4:5], 0, v[2:3]
	s_mov_b64 s[12:13], 0x40000
	v_lshl_add_u64 v[10:11], v[4:5], 0, s[12:13]
	s_mov_b64 s[12:13], 0x60000
	v_lshl_add_u32 v156, v20, 4, 0
	v_lshl_add_u64 v[12:13], v[4:5], 0, s[12:13]
	v_readfirstlane_b32 s12, v156
	v_add_u32_e32 v16, 0x1000, v156
	s_lshl_b32 s2, s24, 11
	v_and_b32_e32 v15, 12, v20
	s_mov_b32 m0, s12
	v_readfirstlane_b32 s12, v16
	v_add_u32_e32 v18, 0x2000, v156
	s_add_u32 s26, s17, s2
	v_lshrrev_b32_e32 v14, 4, v20
	v_lshrrev_b32_e64 v15, v15, s57
	global_load_lds_dwordx4 v[4:5], off
	s_mov_b32 m0, s12
	v_readfirstlane_b32 s12, v18
	s_addc_u32 s27, s18, 0
	v_xor_b32_e32 v14, v15, v14
	global_load_lds_dwordx4 v[8:9], off
	s_mov_b32 m0, s12
	s_mov_b64 s[12:13], 0x40040
	v_add_u32_e32 v18, 0x3000, v156
	v_lshl_add_u64 v[6:7], s[26:27], 0, v[6:7]
	v_lshlrev_b32_e32 v23, 4, v14
	global_load_lds_dwordx4 v[10:11], off
	v_lshl_add_u64 v[10:11], v[4:5], 0, s[12:13]
	v_readfirstlane_b32 s12, v18
	v_lshl_add_u64 v[18:19], s[26:27], 0, v[2:3]
	s_mov_b32 m0, s12
	s_mov_b64 s[12:13], 0x60040
	v_lshl_add_u64 v[18:19], v[18:19], 0, v[0:1]
	v_lshl_add_u64 v[6:7], v[6:7], 0, v[0:1]
	v_and_b32_e32 v0, 48, v23
	v_add_u32_e32 v23, 0x4000, v156
	global_load_lds_dwordx4 v[12:13], off
	v_lshl_add_u64 v[12:13], v[4:5], 0, s[12:13]
	v_readfirstlane_b32 s12, v23
	v_add_u32_e32 v23, 0x5000, v156
	s_mov_b32 m0, s12
	v_readfirstlane_b32 s12, v23
	v_add_u32_e32 v23, 0x6000, v156
	global_load_lds_dwordx4 v[18:19], off
	s_mov_b32 m0, s12
	v_readfirstlane_b32 s12, v23
	v_lshl_add_u64 v[14:15], v[4:5], 0, 64
	global_load_lds_dwordx4 v[6:7], off
	s_mov_b32 m0, s12
	v_lshl_add_u64 v[16:17], v[8:9], 0, 64
	global_load_lds_dwordx4 v[14:15], off
	v_add_u32_e32 v14, 0x7000, v156
	v_lshl_add_u64 v[18:19], v[18:19], 0, 64
	v_readfirstlane_b32 s12, v14
	v_add_u32_e32 v14, 0x8000, v156
	s_mov_b32 m0, s12
	v_readfirstlane_b32 s12, v14
	global_load_lds_dwordx4 v[16:17], off
	s_mov_b32 m0, s12
	v_lshl_add_u64 v[6:7], v[6:7], 0, 64
	global_load_lds_dwordx4 v[10:11], off
	v_add_u32_e32 v10, 0x9000, v156
	v_lshl_add_u64 v[148:149], v[4:5], 0, s[78:79]
	v_readfirstlane_b32 s12, v10
	v_add_u32_e32 v10, 0xa000, v156
	s_mov_b32 m0, s12
	v_readfirstlane_b32 s12, v10
	v_add_u32_e32 v10, 0xb000, v156
	global_load_lds_dwordx4 v[12:13], off
	s_mov_b32 m0, s12
	v_readfirstlane_b32 s12, v10
	global_load_lds_dwordx4 v[18:19], off
	s_mov_b32 m0, s12
	s_mov_b64 s[12:13], 0x60080
	global_load_lds_dwordx4 v[6:7], off
	v_lshl_add_u64 v[146:147], v[4:5], 0, s[12:13]
	s_mov_b64 s[12:13], 0x40080
	v_lshl_add_u64 v[152:153], v[4:5], 0, s[12:13]
	v_lshl_add_u64 v[2:3], s[2:3], 0, v[2:3]
	v_bitop3_b32 v4, v21, 3, v20 bitop3:0x48
	v_lshl_or_b32 v2, v4, 4, v2
	v_lshlrev_b32_e32 v22, 6, v20
	v_lshl_add_u64 v[154:155], s[8:9], 0, v[2:3]
	v_mov_b32_e32 v2, 0
	s_mov_b32 s25, 2
	v_and_b32_e32 v157, 0x13c0, v22
	v_and_b32_e32 v158, 0xffffe3c0, v22
	v_lshl_add_u64 v[150:151], v[8:9], 0, s[78:79]
	s_mov_b32 s2, 0
	s_mov_b64 s[12:13], 0
	v_mov_b32_e32 v3, v2
	v_mov_b32_e32 v4, v2
	v_mov_b32_e32 v5, v2
	v_mov_b32_e32 v6, v2
	v_mov_b32_e32 v7, v2
	v_mov_b32_e32 v8, v2
	v_mov_b32_e32 v9, v2
	v_mov_b32_e32 v10, v2
	v_mov_b32_e32 v11, v2
	v_mov_b32_e32 v12, v2
	v_mov_b32_e32 v13, v2
	v_mov_b32_e32 v14, v2
	v_mov_b32_e32 v15, v2
	v_mov_b32_e32 v16, v2
	v_mov_b32_e32 v17, v2
	v_mov_b32_e32 v18, v2
	v_mov_b32_e32 v19, v2
	v_mov_b32_e32 v20, v2
	v_mov_b32_e32 v21, v2
	v_mov_b32_e32 v22, v2
	v_mov_b32_e32 v23, v2
	v_mov_b32_e32 v24, v2
	v_mov_b32_e32 v25, v2
	v_mov_b32_e32 v26, v2
	v_mov_b32_e32 v27, v2
	v_mov_b32_e32 v28, v2
	v_mov_b32_e32 v29, v2
	v_mov_b32_e32 v30, v2
	v_mov_b32_e32 v31, v2
	v_mov_b32_e32 v32, v2
	v_mov_b32_e32 v33, v2
	v_mov_b32_e32 v34, v2
	v_mov_b32_e32 v35, v2
	v_mov_b32_e32 v36, v2
	v_mov_b32_e32 v37, v2
	v_mov_b32_e32 v38, v2
	v_mov_b32_e32 v39, v2
	v_mov_b32_e32 v40, v2
	v_mov_b32_e32 v41, v2
	v_mov_b32_e32 v42, v2
	v_mov_b32_e32 v43, v2
	v_mov_b32_e32 v44, v2
	v_mov_b32_e32 v45, v2
	v_mov_b32_e32 v46, v2
	v_mov_b32_e32 v47, v2
	v_mov_b32_e32 v48, v2
	v_mov_b32_e32 v49, v2
	v_mov_b32_e32 v50, v2
	v_mov_b32_e32 v51, v2
	v_mov_b32_e32 v52, v2
	v_mov_b32_e32 v53, v2
	v_mov_b32_e32 v54, v2
	v_mov_b32_e32 v55, v2
	v_mov_b32_e32 v56, v2
	v_mov_b32_e32 v57, v2
	v_mov_b32_e32 v58, v2
	v_mov_b32_e32 v59, v2
	v_mov_b32_e32 v60, v2
	v_mov_b32_e32 v61, v2
	v_mov_b32_e32 v62, v2
	v_mov_b32_e32 v63, v2
	v_mov_b32_e32 v64, v2
	v_mov_b32_e32 v65, v2
	v_mov_b32_e32 v66, v2
	v_mov_b32_e32 v67, v2
	v_mov_b32_e32 v68, v2
	v_mov_b32_e32 v69, v2
	v_mov_b32_e32 v70, v2
	v_mov_b32_e32 v71, v2
	v_mov_b32_e32 v72, v2
	v_mov_b32_e32 v73, v2
	v_mov_b32_e32 v74, v2
	v_mov_b32_e32 v75, v2
	v_mov_b32_e32 v76, v2
	v_mov_b32_e32 v77, v2
	v_mov_b32_e32 v78, v2
	v_mov_b32_e32 v79, v2
	v_mov_b32_e32 v80, v2
	v_mov_b32_e32 v81, v2
	v_mov_b32_e32 v82, v2
	v_mov_b32_e32 v83, v2
	v_mov_b32_e32 v84, v2
	v_mov_b32_e32 v85, v2
	v_mov_b32_e32 v86, v2
	v_mov_b32_e32 v87, v2
	v_mov_b32_e32 v88, v2
	v_mov_b32_e32 v89, v2
	v_mov_b32_e32 v90, v2
	v_mov_b32_e32 v91, v2
	v_mov_b32_e32 v92, v2
	v_mov_b32_e32 v93, v2
	v_mov_b32_e32 v94, v2
	v_mov_b32_e32 v95, v2
	v_mov_b32_e32 v96, v2
	v_mov_b32_e32 v97, v2
	v_mov_b32_e32 v98, v2
	v_mov_b32_e32 v99, v2
	v_mov_b32_e32 v100, v2
	v_mov_b32_e32 v101, v2
	v_mov_b32_e32 v102, v2
	v_mov_b32_e32 v103, v2
	v_mov_b32_e32 v104, v2
	v_mov_b32_e32 v105, v2
	v_mov_b32_e32 v106, v2
	v_mov_b32_e32 v107, v2
	v_mov_b32_e32 v108, v2
	v_mov_b32_e32 v109, v2
	v_mov_b32_e32 v110, v2
	v_mov_b32_e32 v111, v2
	v_mov_b32_e32 v112, v2
	v_mov_b32_e32 v113, v2
	v_mov_b32_e32 v114, v2
	v_mov_b32_e32 v115, v2
	v_mov_b32_e32 v116, v2
	v_mov_b32_e32 v117, v2
	v_mov_b32_e32 v118, v2
	v_mov_b32_e32 v119, v2
	v_mov_b32_e32 v120, v2
	v_mov_b32_e32 v121, v2
	v_mov_b32_e32 v122, v2
	v_mov_b32_e32 v123, v2
	v_mov_b32_e32 v124, v2
	v_mov_b32_e32 v125, v2
	v_mov_b32_e32 v126, v2
	v_mov_b32_e32 v127, v2
	v_mov_b32_e32 v128, v2
	v_mov_b32_e32 v129, v2

.LBB0_201:
	s_andn2_b64 vcc, exec, s[0:1]
	s_cbranch_vccnz .LBB0_198
	s_lshr_b32 s1, s18, 5
	s_lshr_b32 s0, s18, 8
	s_xor_b32 s1, s1, s0
	s_and_b32 s1, s1, 1
	s_mulk_i32 s1, 0x120
	s_xor_b32 s2, s18, s1
	s_lshr_b32 s1, s2, 3
	s_and_b32 s0, s15, 7
	s_and_b32 s1, s1, 0xfffff8
	v_mov_b32_e32 v14, v196
	s_or_b32 s0, s1, s0
	s_lshl_b32 s0, s0, 8
	v_lshrrev_b32_e32 v0, 2, v14
	s_lshl_b32 s1, s2, 4
	v_and_b32_e32 v0, 12, v0
	s_and_b32 s2, s1, 0x380
	s_ashr_i32 s1, s0, 31
	v_lshrrev_b32_e64 v0, v0, s57
	s_lshl_b64 s[22:23], s[0:1], 10
	v_xor_b32_e32 v0, v0, v14
	s_add_u32 s22, s8, s22
	v_ashrrev_i32_e32 v2, 2, v14
	v_lshlrev_b32_e32 v0, 4, v0
	s_addc_u32 s23, s9, s23
	s_lshl_b32 s8, s2, 10
	v_and_b32_e32 v0, 48, v0
	v_ashrrev_i32_e32 v3, 31, v2
	v_lshl_add_u32 v19, v14, 4, 0
	s_add_u32 s8, s19, s8
	v_lshl_add_u64 v[6:7], s[22:23], 0, v[0:1]
	v_lshlrev_b64 v[8:9], 10, v[2:3]
	s_mov_b64 s[18:19], 0x10000
	v_readfirstlane_b32 s25, v19
	v_add_u32_e32 v21, 0x1000, v19
	v_lshl_add_u64 v[10:11], v[8:9], 0, s[18:19]
	v_lshl_add_u64 v[2:3], v[6:7], 0, v[8:9]
	s_mov_b32 m0, s25
	v_readfirstlane_b32 s24, v21
	v_add_u32_e32 v20, 0x2000, v19
	v_lshl_add_u64 v[4:5], v[6:7], 0, v[10:11]
	global_load_lds_dwordx4 v[2:3], off
	s_mov_b32 m0, s24
	v_readfirstlane_b32 s23, v20
	v_add_u32_e32 v18, 0x3000, v19
	s_addc_u32 s9, s20, 0
	v_lshrrev_b32_e32 v15, 4, v14
	v_lshl_add_u64 v[6:7], v[2:3], 0, s[76:77]
	s_mov_b64 s[18:19], 0x30000
	v_lshlrev_b32_e32 v24, 6, v14
	v_and_b32_e32 v14, 12, v14
	global_load_lds_dwordx4 v[4:5], off
	s_mov_b32 m0, s23
	v_readfirstlane_b32 s22, v18
	v_add_u32_e32 v28, 0x4000, v19
	v_lshl_add_u64 v[12:13], v[2:3], 0, s[18:19]
	v_lshrrev_b32_e64 v14, v14, s57
	global_load_lds_dwordx4 v[6:7], off
	s_mov_b32 m0, s22
	v_lshl_add_u64 v[6:7], s[8:9], 0, v[8:9]
	v_readfirstlane_b32 s40, v28
	v_add_u32_e32 v29, 0x5000, v19
	v_lshl_add_u64 v[10:11], s[8:9], 0, v[10:11]
	v_xor_b32_e32 v14, v14, v15
	global_load_lds_dwordx4 v[12:13], off
	v_lshl_add_u64 v[8:9], v[6:7], 0, v[0:1]
	s_mov_b32 m0, s40
	v_readfirstlane_b32 s41, v29
	v_add_u32_e32 v27, 0x6000, v19
	v_lshlrev_b32_e32 v25, 4, v14
	v_lshl_add_u64 v[6:7], v[10:11], 0, v[0:1]
	global_load_lds_dwordx4 v[8:9], off
	s_mov_b32 m0, s41
	v_readfirstlane_b32 s39, v27
	v_add_u32_e32 v26, 0x7000, v19
	v_lshl_add_u64 v[14:15], v[2:3], 0, 64
	v_and_b32_e32 v0, 48, v25
	global_load_lds_dwordx4 v[6:7], off
	s_mov_b32 m0, s39
	v_readfirstlane_b32 s38, v26
	v_add_u32_e32 v25, 0x8000, v19
	v_lshl_add_u64 v[16:17], v[4:5], 0, 64
	global_load_lds_dwordx4 v[14:15], off
	s_mov_b32 m0, s38
	v_readfirstlane_b32 s37, v25
	v_lshl_add_u64 v[22:23], v[2:3], 0, s[96:97]
	global_load_lds_dwordx4 v[16:17], off
	s_mov_b32 m0, s37
	s_mov_b64 s[18:19], 0x30040
	global_load_lds_dwordx4 v[22:23], off
	v_add_u32_e32 v22, 0x9000, v19
	v_add_u32_e32 v23, 0xa000, v19
	v_readfirstlane_b32 s26, v22
	v_and_b32_e32 v36, 0x13c0, v24
	v_lshl_add_u64 v[12:13], v[2:3], 0, s[18:19]
	s_mov_b32 m0, s26
	v_and_b32_e32 v46, 0xffffe3c0, v24
	v_readfirstlane_b32 s27, v23
	v_add_u32_e32 v24, 0xb000, v19
	v_lshl_add_u64 v[10:11], v[8:9], 0, 64
	global_load_lds_dwordx4 v[12:13], off
	s_mov_b32 m0, s27
	v_readfirstlane_b32 s36, v24
	v_lshl_add_u64 v[12:13], v[6:7], 0, 64
	global_load_lds_dwordx4 v[10:11], off
	s_mov_b32 m0, s36
	s_mov_b64 s[8:9], 0x30080
	global_load_lds_dwordx4 v[12:13], off
	v_add_u32_e32 v12, 0xc000, v19
	v_lshl_add_u64 v[16:17], v[2:3], 0, s[8:9]
	v_readfirstlane_b32 s8, v12
	v_lshl_add_u64 v[14:15], v[2:3], 0, s[78:79]
	s_waitcnt vmcnt(6) lgkmcnt(0)
	s_barrier
	s_mov_b32 m0, s8
	v_add_u32_e32 v13, 0xd000, v19
	global_load_lds_dwordx4 v[14:15], off
	v_readfirstlane_b32 s9, v13
	v_add_u32_e32 v14, 0xe000, v19
	v_lshl_add_u64 v[32:33], v[4:5], 0, s[78:79]
	s_mov_b32 m0, s9
	v_readfirstlane_b32 s19, v14
	v_add_u32_e32 v15, 0xf000, v19
	v_lshl_add_u64 v[34:35], v[2:3], 0, s[90:91]
	global_load_lds_dwordx4 v[32:33], off
	s_mov_b32 m0, s19
	v_readfirstlane_b32 s18, v15
	global_load_lds_dwordx4 v[34:35], off
	s_mov_b64 s[20:21], 0x200c0
	s_mov_b32 m0, s18
	v_lshl_add_u64 v[166:167], v[2:3], 0, s[20:21]
	global_load_lds_dwordx4 v[16:17], off
	s_mov_b64 s[20:21], 0x300c0
	v_add_u32_e32 v16, 0x10000, v19
	v_lshl_add_u64 v[168:169], v[2:3], 0, s[20:21]
	v_readfirstlane_b32 s20, v16
	v_add_u32_e32 v17, 0x11000, v19
	v_lshl_add_u64 v[10:11], v[8:9], 0, s[78:79]
	s_mov_b32 m0, s20
	v_readfirstlane_b32 s21, v17
	v_lshl_add_u64 v[30:31], v[6:7], 0, s[78:79]
	global_load_lds_dwordx4 v[10:11], off
	s_mov_b32 m0, s21
	v_add3_u32 v10, 0, v36, v0
	global_load_lds_dwordx4 v[30:31], off
	v_add3_u32 v0, 0, v46, v0
	v_lshl_add_u64 v[162:163], v[2:3], 0, s[84:85]
	ds_read_b128 v[30:33], v10 offset:16384
	ds_read_b128 v[34:37], v10 offset:17408
	ds_read_b128 v[38:41], v10 offset:18432
	ds_read_b128 v[42:45], v10 offset:19456
	ds_read_b128 v[46:49], v0
	ds_read_b128 v[50:53], v0 offset:1024
	ds_read_b128 v[54:57], v0 offset:2048
	ds_read_b128 v[58:61], v0 offset:3072
	ds_read_b128 v[110:113], v0 offset:4096
	ds_read_b128 v[114:117], v0 offset:5120
	ds_read_b128 v[118:121], v0 offset:6144
	ds_read_b128 v[122:125], v0 offset:7168
	s_waitcnt vmcnt(6) lgkmcnt(0)
	s_barrier
	s_mov_b32 m0, s25
	v_lshl_add_u64 v[164:165], v[4:5], 0, s[84:85]
	global_load_lds_dwordx4 v[162:163], off
	s_mov_b32 m0, s24
	v_lshl_add_u64 v[170:171], v[8:9], 0, s[84:85]
	global_load_lds_dwordx4 v[164:165], off
	s_mov_b32 m0, s23
	v_lshl_add_u64 v[172:173], v[6:7], 0, s[84:85]
	global_load_lds_dwordx4 v[166:167], off
	s_mov_b32 m0, s22
	s_waitcnt lgkmcnt(0)
	v_mfma_f32_16x16x32_bf16 v[62:65], v[30:33], v[46:49], 0
	global_load_lds_dwordx4 v[168:169], off
	s_mov_b32 m0, s40
	v_mfma_f32_16x16x32_bf16 v[66:69], v[34:37], v[46:49], 0
	global_load_lds_dwordx4 v[170:171], off
	s_mov_b32 m0, s41
	v_mfma_f32_16x16x32_bf16 v[70:73], v[38:41], v[46:49], 0
	global_load_lds_dwordx4 v[172:173], off
	s_mov_b32 s44, s59
	v_mfma_f32_16x16x32_bf16 v[46:49], v[42:45], v[46:49], 0
	s_mov_b64 s[58:59], 0x100
	v_lshl_add_u64 v[190:191], v[2:3], 0, s[58:59]
	s_mov_b32 m0, s39
	v_mfma_f32_16x16x32_bf16 v[74:77], v[30:33], v[50:53], 0
	v_lshl_add_u64 v[192:193], v[4:5], 0, s[58:59]
	s_mov_b64 s[42:43], 0x20100
	v_lshl_add_u64 v[194:195], v[2:3], 0, s[42:43]
	v_mfma_f32_16x16x32_bf16 v[78:81], v[34:37], v[50:53], 0
	s_mov_b64 s[42:43], 0x30100
	v_lshl_add_u64 v[214:215], v[2:3], 0, s[42:43]
	v_lshl_add_u64 v[216:217], v[8:9], 0, s[58:59]
	v_mfma_f32_16x16x32_bf16 v[82:85], v[38:41], v[50:53], 0
	v_lshl_add_u64 v[218:219], v[6:7], 0, s[58:59]
	v_add_u32_e32 v11, 0xc000, v10
	s_mov_b64 s[58:59], 0x140
	v_mfma_f32_16x16x32_bf16 v[50:53], v[42:45], v[50:53], 0
	s_mov_b64 s[42:43], 0x20140
	s_lshl_b64 s[0:1], s[0:1], 11
	s_add_u32 s0, s17, s0
	v_mfma_f32_16x16x32_bf16 v[86:89], v[30:33], v[54:57], 0
	s_addc_u32 s1, s16, s1
	s_lshl_b32 s2, s2, 1
	s_add_u32 s0, s0, s2
	v_mfma_f32_16x16x32_bf16 v[90:93], v[34:37], v[54:57], 0
	s_addc_u32 s1, s1, 0
	s_movk_i32 s57, 0x1320
	s_mov_b32 s56, 0x800000
	v_mfma_f32_16x16x32_bf16 v[94:97], v[38:41], v[54:57], 0
	v_readlane_b32 s88, v225, 56
	v_mfma_f32_16x16x32_bf16 v[54:57], v[42:45], v[54:57], 0
	v_mfma_f32_16x16x32_bf16 v[98:101], v[30:33], v[58:61], 0
	v_mfma_f32_16x16x32_bf16 v[102:105], v[34:37], v[58:61], 0
	v_mfma_f32_16x16x32_bf16 v[106:109], v[38:41], v[58:61], 0
	v_mfma_f32_16x16x32_bf16 v[58:61], v[42:45], v[58:61], 0
	v_mfma_f32_16x16x32_bf16 v[126:129], v[30:33], v[110:113], 0
	v_mfma_f32_16x16x32_bf16 v[130:133], v[34:37], v[110:113], 0
	v_mfma_f32_16x16x32_bf16 v[134:137], v[38:41], v[110:113], 0
	v_mfma_f32_16x16x32_bf16 v[110:113], v[42:45], v[110:113], 0
	v_mfma_f32_16x16x32_bf16 v[138:141], v[30:33], v[114:117], 0
	v_mfma_f32_16x16x32_bf16 v[142:145], v[34:37], v[114:117], 0
	v_mfma_f32_16x16x32_bf16 v[146:149], v[38:41], v[114:117], 0
	v_mfma_f32_16x16x32_bf16 v[114:117], v[42:45], v[114:117], 0
	v_mfma_f32_16x16x32_bf16 v[150:153], v[30:33], v[118:121], 0
	v_mfma_f32_16x16x32_bf16 v[154:157], v[34:37], v[118:121], 0
	v_mfma_f32_16x16x32_bf16 v[158:161], v[38:41], v[118:121], 0
	v_mfma_f32_16x16x32_bf16 v[118:121], v[42:45], v[118:121], 0
	v_mfma_f32_16x16x32_bf16 v[30:33], v[30:33], v[122:125], 0
	v_mfma_f32_16x16x32_bf16 v[34:37], v[34:37], v[122:125], 0
	v_mfma_f32_16x16x32_bf16 v[38:41], v[38:41], v[122:125], 0
	v_mfma_f32_16x16x32_bf16 v[42:45], v[42:45], v[122:125], 0
	ds_read_b128 v[122:125], v10 offset:40960
	ds_read_b128 v[162:165], v10 offset:41984
	ds_read_b128 v[166:169], v10 offset:43008
	ds_read_b128 v[170:173], v10 offset:44032
	ds_read_b128 v[174:177], v0 offset:24576
	ds_read_b128 v[178:181], v0 offset:25600
	ds_read_b128 v[182:185], v0 offset:26624
	ds_read_b128 v[186:189], v0 offset:27648
	s_waitcnt lgkmcnt(0)
	v_mfma_f32_16x16x32_bf16 v[62:65], v[122:125], v[174:177], v[62:65]
	v_mfma_f32_16x16x32_bf16 v[66:69], v[162:165], v[174:177], v[66:69]
	v_mfma_f32_16x16x32_bf16 v[70:73], v[166:169], v[174:177], v[70:73]
	v_mfma_f32_16x16x32_bf16 v[46:49], v[170:173], v[174:177], v[46:49]
	v_mfma_f32_16x16x32_bf16 v[74:77], v[122:125], v[178:181], v[74:77]
	v_mfma_f32_16x16x32_bf16 v[78:81], v[162:165], v[178:181], v[78:81]
	v_mfma_f32_16x16x32_bf16 v[82:85], v[166:169], v[178:181], v[82:85]
	v_mfma_f32_16x16x32_bf16 v[50:53], v[170:173], v[178:181], v[50:53]
	v_mfma_f32_16x16x32_bf16 v[86:89], v[122:125], v[182:185], v[86:89]
	v_mfma_f32_16x16x32_bf16 v[90:93], v[162:165], v[182:185], v[90:93]
	v_mfma_f32_16x16x32_bf16 v[94:97], v[166:169], v[182:185], v[94:97]
	v_mfma_f32_16x16x32_bf16 v[54:57], v[170:173], v[182:185], v[54:57]
	v_mfma_f32_16x16x32_bf16 v[98:101], v[122:125], v[186:189], v[98:101]
	v_mfma_f32_16x16x32_bf16 v[102:105], v[162:165], v[186:189], v[102:105]
	v_mfma_f32_16x16x32_bf16 v[106:109], v[166:169], v[186:189], v[106:109]
	v_mfma_f32_16x16x32_bf16 v[58:61], v[170:173], v[186:189], v[58:61]
	ds_read_b128 v[174:177], v0 offset:28672
	ds_read_b128 v[178:181], v0 offset:29696
	ds_read_b128 v[182:185], v0 offset:30720
	ds_read_b128 v[186:189], v0 offset:31744
	s_waitcnt vmcnt(6) lgkmcnt(0)
	s_barrier
	global_load_lds_dwordx4 v[190:191], off
	s_mov_b32 m0, s38
	s_waitcnt lgkmcnt(0)
	v_mfma_f32_16x16x32_bf16 v[126:129], v[122:125], v[174:177], v[126:129]
	global_load_lds_dwordx4 v[192:193], off
	s_mov_b32 m0, s37
	v_mfma_f32_16x16x32_bf16 v[130:133], v[162:165], v[174:177], v[130:133]
	global_load_lds_dwordx4 v[194:195], off
	s_mov_b32 m0, s26
	v_mfma_f32_16x16x32_bf16 v[134:137], v[166:169], v[174:177], v[134:137]
	global_load_lds_dwordx4 v[214:215], off
	s_mov_b32 m0, s27
	v_mfma_f32_16x16x32_bf16 v[110:113], v[170:173], v[174:177], v[110:113]
	global_load_lds_dwordx4 v[216:217], off
	s_mov_b32 m0, s36
	v_mfma_f32_16x16x32_bf16 v[138:141], v[122:125], v[178:181], v[138:141]
	global_load_lds_dwordx4 v[218:219], off
	v_lshl_add_u64 v[190:191], v[2:3], 0, s[58:59]
	v_mfma_f32_16x16x32_bf16 v[142:145], v[162:165], v[178:181], v[142:145]
	s_mov_b32 m0, s8
	v_lshl_add_u64 v[192:193], v[4:5], 0, s[58:59]
	v_lshl_add_u64 v[194:195], v[2:3], 0, s[42:43]
	v_mfma_f32_16x16x32_bf16 v[146:149], v[166:169], v[178:181], v[146:149]
	s_mov_b64 s[42:43], 0x30140
	v_lshl_add_u64 v[214:215], v[2:3], 0, s[42:43]
	v_lshl_add_u64 v[216:217], v[8:9], 0, s[58:59]
	v_mfma_f32_16x16x32_bf16 v[114:117], v[170:173], v[178:181], v[114:117]
	v_lshl_add_u64 v[218:219], v[6:7], 0, s[58:59]
	s_mov_b64 s[58:59], 0x180
	s_mov_b64 s[42:43], 0x20180
	v_mfma_f32_16x16x32_bf16 v[150:153], v[122:125], v[182:185], v[150:153]
	v_mfma_f32_16x16x32_bf16 v[154:157], v[162:165], v[182:185], v[154:157]
	v_mfma_f32_16x16x32_bf16 v[158:161], v[166:169], v[182:185], v[158:161]
	v_mfma_f32_16x16x32_bf16 v[118:121], v[170:173], v[182:185], v[118:121]
	v_mfma_f32_16x16x32_bf16 v[30:33], v[122:125], v[186:189], v[30:33]
	v_mfma_f32_16x16x32_bf16 v[34:37], v[162:165], v[186:189], v[34:37]
	v_mfma_f32_16x16x32_bf16 v[38:41], v[166:169], v[186:189], v[38:41]
	v_mfma_f32_16x16x32_bf16 v[42:45], v[170:173], v[186:189], v[42:45]
	ds_read_b128 v[122:125], v11 offset:16384
	ds_read_b128 v[162:165], v11 offset:17408
	ds_read_b128 v[166:169], v11 offset:18432
	ds_read_b128 v[170:173], v11 offset:19456
	ds_read_b128 v[174:177], v0 offset:49152
	ds_read_b128 v[178:181], v0 offset:50176
	ds_read_b128 v[182:185], v0 offset:51200
	ds_read_b128 v[186:189], v0 offset:52224
	s_waitcnt lgkmcnt(0)
	v_mfma_f32_16x16x32_bf16 v[62:65], v[122:125], v[174:177], v[62:65]
	v_mfma_f32_16x16x32_bf16 v[66:69], v[162:165], v[174:177], v[66:69]
	v_mfma_f32_16x16x32_bf16 v[70:73], v[166:169], v[174:177], v[70:73]
	v_mfma_f32_16x16x32_bf16 v[46:49], v[170:173], v[174:177], v[46:49]
	v_mfma_f32_16x16x32_bf16 v[74:77], v[122:125], v[178:181], v[74:77]
	v_mfma_f32_16x16x32_bf16 v[78:81], v[162:165], v[178:181], v[78:81]
	v_mfma_f32_16x16x32_bf16 v[82:85], v[166:169], v[178:181], v[82:85]
	v_mfma_f32_16x16x32_bf16 v[50:53], v[170:173], v[178:181], v[50:53]
	v_mfma_f32_16x16x32_bf16 v[86:89], v[122:125], v[182:185], v[86:89]
	v_mfma_f32_16x16x32_bf16 v[90:93], v[162:165], v[182:185], v[90:93]
	v_mfma_f32_16x16x32_bf16 v[94:97], v[166:169], v[182:185], v[94:97]
	v_mfma_f32_16x16x32_bf16 v[54:57], v[170:173], v[182:185], v[54:57]
	v_mfma_f32_16x16x32_bf16 v[98:101], v[122:125], v[186:189], v[98:101]
	v_mfma_f32_16x16x32_bf16 v[102:105], v[162:165], v[186:189], v[102:105]
	v_mfma_f32_16x16x32_bf16 v[106:109], v[166:169], v[186:189], v[106:109]
	v_mfma_f32_16x16x32_bf16 v[58:61], v[170:173], v[186:189], v[58:61]
	ds_read_b128 v[174:177], v0 offset:53248
	ds_read_b128 v[178:181], v0 offset:54272
	ds_read_b128 v[182:185], v0 offset:55296
	ds_read_b128 v[186:189], v0 offset:56320
	s_waitcnt vmcnt(6) lgkmcnt(0)
	s_barrier
	global_load_lds_dwordx4 v[190:191], off
	s_mov_b32 m0, s9
	s_waitcnt lgkmcnt(0)
	v_mfma_f32_16x16x32_bf16 v[126:129], v[122:125], v[174:177], v[126:129]
	global_load_lds_dwordx4 v[192:193], off
	s_mov_b32 m0, s19
	v_mfma_f32_16x16x32_bf16 v[130:133], v[162:165], v[174:177], v[130:133]
	global_load_lds_dwordx4 v[194:195], off
	s_mov_b32 m0, s18
	v_mfma_f32_16x16x32_bf16 v[134:137], v[166:169], v[174:177], v[134:137]
	global_load_lds_dwordx4 v[214:215], off
	s_mov_b32 m0, s20
	v_mfma_f32_16x16x32_bf16 v[110:113], v[170:173], v[174:177], v[110:113]
	global_load_lds_dwordx4 v[216:217], off
	s_mov_b32 m0, s21
	v_mfma_f32_16x16x32_bf16 v[138:141], v[122:125], v[178:181], v[138:141]
	global_load_lds_dwordx4 v[218:219], off
	v_lshl_add_u64 v[190:191], v[2:3], 0, s[58:59]
	v_mfma_f32_16x16x32_bf16 v[142:145], v[162:165], v[178:181], v[142:145]
	s_mov_b32 m0, s25
	v_lshl_add_u64 v[192:193], v[4:5], 0, s[58:59]
	v_lshl_add_u64 v[194:195], v[2:3], 0, s[42:43]
	v_mfma_f32_16x16x32_bf16 v[146:149], v[166:169], v[178:181], v[146:149]
	s_mov_b64 s[42:43], 0x30180
	v_lshl_add_u64 v[214:215], v[2:3], 0, s[42:43]
	v_lshl_add_u64 v[216:217], v[8:9], 0, s[58:59]
	v_mfma_f32_16x16x32_bf16 v[114:117], v[170:173], v[178:181], v[114:117]
	v_lshl_add_u64 v[218:219], v[6:7], 0, s[58:59]
	s_mov_b64 s[42:43], 0x1c0
	s_mov_b64 s[58:59], 0x340
	v_mfma_f32_16x16x32_bf16 v[150:153], v[122:125], v[182:185], v[150:153]
	v_mfma_f32_16x16x32_bf16 v[154:157], v[162:165], v[182:185], v[154:157]
	v_mfma_f32_16x16x32_bf16 v[158:161], v[166:169], v[182:185], v[158:161]
	v_mfma_f32_16x16x32_bf16 v[118:121], v[170:173], v[182:185], v[118:121]
	v_mfma_f32_16x16x32_bf16 v[30:33], v[122:125], v[186:189], v[30:33]
	v_mfma_f32_16x16x32_bf16 v[34:37], v[162:165], v[186:189], v[34:37]
	v_mfma_f32_16x16x32_bf16 v[38:41], v[166:169], v[186:189], v[38:41]
	v_mfma_f32_16x16x32_bf16 v[42:45], v[170:173], v[186:189], v[42:45]
	ds_read_b128 v[122:125], v10 offset:16384
	ds_read_b128 v[162:165], v10 offset:17408
	ds_read_b128 v[166:169], v10 offset:18432
	ds_read_b128 v[170:173], v10 offset:19456
	ds_read_b128 v[174:177], v0
	ds_read_b128 v[178:181], v0 offset:1024
	ds_read_b128 v[182:185], v0 offset:2048
	ds_read_b128 v[186:189], v0 offset:3072
	s_waitcnt lgkmcnt(0)
	v_mfma_f32_16x16x32_bf16 v[62:65], v[122:125], v[174:177], v[62:65]
	v_mfma_f32_16x16x32_bf16 v[66:69], v[162:165], v[174:177], v[66:69]
	v_mfma_f32_16x16x32_bf16 v[70:73], v[166:169], v[174:177], v[70:73]
	v_mfma_f32_16x16x32_bf16 v[46:49], v[170:173], v[174:177], v[46:49]
	v_mfma_f32_16x16x32_bf16 v[74:77], v[122:125], v[178:181], v[74:77]
	v_mfma_f32_16x16x32_bf16 v[78:81], v[162:165], v[178:181], v[78:81]
	v_mfma_f32_16x16x32_bf16 v[82:85], v[166:169], v[178:181], v[82:85]
	v_mfma_f32_16x16x32_bf16 v[50:53], v[170:173], v[178:181], v[50:53]
	v_mfma_f32_16x16x32_bf16 v[86:89], v[122:125], v[182:185], v[86:89]
	v_mfma_f32_16x16x32_bf16 v[90:93], v[162:165], v[182:185], v[90:93]
	v_mfma_f32_16x16x32_bf16 v[94:97], v[166:169], v[182:185], v[94:97]
	v_mfma_f32_16x16x32_bf16 v[54:57], v[170:173], v[182:185], v[54:57]
	v_mfma_f32_16x16x32_bf16 v[98:101], v[122:125], v[186:189], v[98:101]
	v_mfma_f32_16x16x32_bf16 v[102:105], v[162:165], v[186:189], v[102:105]
	v_mfma_f32_16x16x32_bf16 v[106:109], v[166:169], v[186:189], v[106:109]
	v_mfma_f32_16x16x32_bf16 v[58:61], v[170:173], v[186:189], v[58:61]
	ds_read_b128 v[174:177], v0 offset:4096
	ds_read_b128 v[178:181], v0 offset:5120
	ds_read_b128 v[182:185], v0 offset:6144
	ds_read_b128 v[186:189], v0 offset:7168
	s_waitcnt vmcnt(6) lgkmcnt(0)
	s_barrier
	global_load_lds_dwordx4 v[190:191], off
	s_mov_b32 m0, s24
	s_waitcnt lgkmcnt(0)
	v_mfma_f32_16x16x32_bf16 v[126:129], v[122:125], v[174:177], v[126:129]
	global_load_lds_dwordx4 v[192:193], off
	s_mov_b32 m0, s23
	v_mfma_f32_16x16x32_bf16 v[130:133], v[162:165], v[174:177], v[130:133]
	global_load_lds_dwordx4 v[194:195], off
	s_mov_b32 m0, s22
	v_mfma_f32_16x16x32_bf16 v[134:137], v[166:169], v[174:177], v[134:137]
	global_load_lds_dwordx4 v[214:215], off
	s_mov_b32 m0, s40
	v_mfma_f32_16x16x32_bf16 v[110:113], v[170:173], v[174:177], v[110:113]
	global_load_lds_dwordx4 v[216:217], off
	s_mov_b32 m0, s41
	v_mfma_f32_16x16x32_bf16 v[138:141], v[122:125], v[178:181], v[138:141]
	global_load_lds_dwordx4 v[218:219], off
	v_lshl_add_u64 v[190:191], v[2:3], 0, s[42:43]
	v_mfma_f32_16x16x32_bf16 v[142:145], v[162:165], v[178:181], v[142:145]
	s_mov_b32 m0, s39
	v_lshl_add_u64 v[192:193], v[4:5], 0, s[42:43]
	s_mov_b64 s[24:25], 0x201c0
	v_mfma_f32_16x16x32_bf16 v[146:149], v[166:169], v[178:181], v[146:149]
	v_lshl_add_u64 v[194:195], v[2:3], 0, s[24:25]
	s_mov_b64 s[22:23], 0x301c0
	v_lshl_add_u64 v[214:215], v[2:3], 0, s[22:23]
	v_mfma_f32_16x16x32_bf16 v[114:117], v[170:173], v[178:181], v[114:117]
	v_lshl_add_u64 v[216:217], v[8:9], 0, s[42:43]
	v_lshl_add_u64 v[218:219], v[6:7], 0, s[42:43]
	s_mov_b64 s[24:25], 0x200
	v_mfma_f32_16x16x32_bf16 v[150:153], v[122:125], v[182:185], v[150:153]
	s_mov_b64 s[22:23], 0x20200
	s_mov_b64 s[40:41], 0x20300
	v_readfirstlane_b32 s39, v15
	v_mfma_f32_16x16x32_bf16 v[154:157], v[162:165], v[182:185], v[154:157]
	s_mov_b64 s[42:43], 0x300
	v_mfma_f32_16x16x32_bf16 v[158:161], v[166:169], v[182:185], v[158:161]
	v_mfma_f32_16x16x32_bf16 v[118:121], v[170:173], v[182:185], v[118:121]
	v_mfma_f32_16x16x32_bf16 v[30:33], v[122:125], v[186:189], v[30:33]
	v_mfma_f32_16x16x32_bf16 v[34:37], v[162:165], v[186:189], v[34:37]
	v_mfma_f32_16x16x32_bf16 v[38:41], v[166:169], v[186:189], v[38:41]
	v_mfma_f32_16x16x32_bf16 v[42:45], v[170:173], v[186:189], v[42:45]
	ds_read_b128 v[122:125], v10 offset:40960
	ds_read_b128 v[162:165], v10 offset:41984
	ds_read_b128 v[166:169], v10 offset:43008
	ds_read_b128 v[170:173], v10 offset:44032
	ds_read_b128 v[174:177], v0 offset:24576
	ds_read_b128 v[178:181], v0 offset:25600
	ds_read_b128 v[182:185], v0 offset:26624
	ds_read_b128 v[186:189], v0 offset:27648
	s_waitcnt lgkmcnt(0)
	v_mfma_f32_16x16x32_bf16 v[62:65], v[122:125], v[174:177], v[62:65]
	v_mfma_f32_16x16x32_bf16 v[66:69], v[162:165], v[174:177], v[66:69]
	v_mfma_f32_16x16x32_bf16 v[70:73], v[166:169], v[174:177], v[70:73]
	v_mfma_f32_16x16x32_bf16 v[46:49], v[170:173], v[174:177], v[46:49]
	v_mfma_f32_16x16x32_bf16 v[74:77], v[122:125], v[178:181], v[74:77]
	v_mfma_f32_16x16x32_bf16 v[78:81], v[162:165], v[178:181], v[78:81]
	v_mfma_f32_16x16x32_bf16 v[82:85], v[166:169], v[178:181], v[82:85]
	v_mfma_f32_16x16x32_bf16 v[50:53], v[170:173], v[178:181], v[50:53]
	v_mfma_f32_16x16x32_bf16 v[86:89], v[122:125], v[182:185], v[86:89]
	v_mfma_f32_16x16x32_bf16 v[90:93], v[162:165], v[182:185], v[90:93]
	v_mfma_f32_16x16x32_bf16 v[94:97], v[166:169], v[182:185], v[94:97]
	v_mfma_f32_16x16x32_bf16 v[54:57], v[170:173], v[182:185], v[54:57]
	v_mfma_f32_16x16x32_bf16 v[98:101], v[122:125], v[186:189], v[98:101]
	v_mfma_f32_16x16x32_bf16 v[102:105], v[162:165], v[186:189], v[102:105]
	v_mfma_f32_16x16x32_bf16 v[106:109], v[166:169], v[186:189], v[106:109]
	v_mfma_f32_16x16x32_bf16 v[58:61], v[170:173], v[186:189], v[58:61]
	ds_read_b128 v[174:177], v0 offset:28672
	ds_read_b128 v[178:181], v0 offset:29696
	ds_read_b128 v[182:185], v0 offset:30720
	ds_read_b128 v[186:189], v0 offset:31744
	s_waitcnt vmcnt(6) lgkmcnt(0)
	s_barrier
	global_load_lds_dwordx4 v[190:191], off
	s_mov_b32 m0, s38
	s_waitcnt lgkmcnt(0)
	v_mfma_f32_16x16x32_bf16 v[126:129], v[122:125], v[174:177], v[126:129]
	global_load_lds_dwordx4 v[192:193], off
	s_mov_b32 m0, s37
	v_mfma_f32_16x16x32_bf16 v[130:133], v[162:165], v[174:177], v[130:133]
	global_load_lds_dwordx4 v[194:195], off
	s_mov_b32 m0, s26
	v_mfma_f32_16x16x32_bf16 v[134:137], v[166:169], v[174:177], v[134:137]
	global_load_lds_dwordx4 v[214:215], off
	s_mov_b32 m0, s27
	v_mfma_f32_16x16x32_bf16 v[110:113], v[170:173], v[174:177], v[110:113]
	global_load_lds_dwordx4 v[216:217], off
	s_mov_b32 m0, s36
	v_mfma_f32_16x16x32_bf16 v[138:141], v[122:125], v[178:181], v[138:141]
	global_load_lds_dwordx4 v[218:219], off
	v_lshl_add_u64 v[190:191], v[2:3], 0, s[24:25]
	v_mfma_f32_16x16x32_bf16 v[142:145], v[162:165], v[178:181], v[142:145]
	s_mov_b32 m0, s8
	v_lshl_add_u64 v[192:193], v[4:5], 0, s[24:25]
	v_lshl_add_u64 v[194:195], v[2:3], 0, s[22:23]
	v_mfma_f32_16x16x32_bf16 v[146:149], v[166:169], v[178:181], v[146:149]
	s_mov_b64 s[22:23], 0x30200
	v_lshl_add_u64 v[214:215], v[2:3], 0, s[22:23]
	v_lshl_add_u64 v[216:217], v[8:9], 0, s[24:25]
	v_mfma_f32_16x16x32_bf16 v[114:117], v[170:173], v[178:181], v[114:117]
	v_lshl_add_u64 v[218:219], v[6:7], 0, s[24:25]
	s_mov_b64 s[22:23], 0x240
	v_readfirstlane_b32 s24, v25
	v_mfma_f32_16x16x32_bf16 v[150:153], v[122:125], v[182:185], v[150:153]
	s_mov_b64 s[26:27], 0x202c0
	v_readfirstlane_b32 s25, v22
	s_mov_b64 s[36:37], 0x2c0
	v_mfma_f32_16x16x32_bf16 v[154:157], v[162:165], v[182:185], v[154:157]
	v_readfirstlane_b32 s38, v14
	v_mfma_f32_16x16x32_bf16 v[158:161], v[166:169], v[182:185], v[158:161]
	v_mfma_f32_16x16x32_bf16 v[118:121], v[170:173], v[182:185], v[118:121]
	v_mfma_f32_16x16x32_bf16 v[30:33], v[122:125], v[186:189], v[30:33]
	v_mfma_f32_16x16x32_bf16 v[34:37], v[162:165], v[186:189], v[34:37]
	v_mfma_f32_16x16x32_bf16 v[38:41], v[166:169], v[186:189], v[38:41]
	v_mfma_f32_16x16x32_bf16 v[42:45], v[170:173], v[186:189], v[42:45]
	ds_read_b128 v[122:125], v11 offset:16384
	ds_read_b128 v[162:165], v11 offset:17408
	ds_read_b128 v[166:169], v11 offset:18432
	ds_read_b128 v[170:173], v11 offset:19456
	ds_read_b128 v[174:177], v0 offset:49152
	ds_read_b128 v[178:181], v0 offset:50176
	ds_read_b128 v[182:185], v0 offset:51200
	ds_read_b128 v[186:189], v0 offset:52224
	s_waitcnt lgkmcnt(0)
	v_mfma_f32_16x16x32_bf16 v[62:65], v[122:125], v[174:177], v[62:65]
	v_mfma_f32_16x16x32_bf16 v[66:69], v[162:165], v[174:177], v[66:69]
	v_mfma_f32_16x16x32_bf16 v[70:73], v[166:169], v[174:177], v[70:73]
	v_mfma_f32_16x16x32_bf16 v[46:49], v[170:173], v[174:177], v[46:49]
	v_mfma_f32_16x16x32_bf16 v[74:77], v[122:125], v[178:181], v[74:77]
	v_mfma_f32_16x16x32_bf16 v[78:81], v[162:165], v[178:181], v[78:81]
	v_mfma_f32_16x16x32_bf16 v[82:85], v[166:169], v[178:181], v[82:85]
	v_mfma_f32_16x16x32_bf16 v[50:53], v[170:173], v[178:181], v[50:53]
	v_mfma_f32_16x16x32_bf16 v[86:89], v[122:125], v[182:185], v[86:89]
	v_mfma_f32_16x16x32_bf16 v[90:93], v[162:165], v[182:185], v[90:93]
	v_mfma_f32_16x16x32_bf16 v[94:97], v[166:169], v[182:185], v[94:97]
	v_mfma_f32_16x16x32_bf16 v[54:57], v[170:173], v[182:185], v[54:57]
	v_mfma_f32_16x16x32_bf16 v[98:101], v[122:125], v[186:189], v[98:101]
	v_mfma_f32_16x16x32_bf16 v[102:105], v[162:165], v[186:189], v[102:105]
	v_mfma_f32_16x16x32_bf16 v[106:109], v[166:169], v[186:189], v[106:109]
	v_mfma_f32_16x16x32_bf16 v[58:61], v[170:173], v[186:189], v[58:61]
	ds_read_b128 v[174:177], v0 offset:53248
	ds_read_b128 v[178:181], v0 offset:54272
	ds_read_b128 v[182:185], v0 offset:55296
	ds_read_b128 v[186:189], v0 offset:56320
	s_waitcnt vmcnt(6) lgkmcnt(0)
	s_barrier
	global_load_lds_dwordx4 v[190:191], off
	s_mov_b32 m0, s9
	s_waitcnt lgkmcnt(0)
	v_mfma_f32_16x16x32_bf16 v[126:129], v[122:125], v[174:177], v[126:129]
	global_load_lds_dwordx4 v[192:193], off
	s_mov_b32 m0, s19
	v_mfma_f32_16x16x32_bf16 v[130:133], v[162:165], v[174:177], v[130:133]
	global_load_lds_dwordx4 v[194:195], off
	s_mov_b32 m0, s18
	v_mfma_f32_16x16x32_bf16 v[134:137], v[166:169], v[174:177], v[134:137]
	global_load_lds_dwordx4 v[214:215], off
	s_mov_b32 m0, s20
	v_mfma_f32_16x16x32_bf16 v[110:113], v[170:173], v[174:177], v[110:113]
	global_load_lds_dwordx4 v[216:217], off
	s_mov_b32 m0, s21
	v_mfma_f32_16x16x32_bf16 v[138:141], v[122:125], v[178:181], v[138:141]
	global_load_lds_dwordx4 v[218:219], off
	s_mov_b64 s[8:9], 0x20240
	v_mfma_f32_16x16x32_bf16 v[142:145], v[162:165], v[178:181], v[142:145]
	v_lshl_add_u64 v[194:195], v[2:3], 0, s[8:9]
	s_mov_b64 s[8:9], 0x30240
	v_lshl_add_u64 v[214:215], v[2:3], 0, s[8:9]
	v_mfma_f32_16x16x32_bf16 v[146:149], v[166:169], v[178:181], v[146:149]
	v_readfirstlane_b32 s8, v19
	v_lshl_add_u64 v[190:191], v[2:3], 0, s[22:23]
	s_mov_b32 m0, s8
	v_mfma_f32_16x16x32_bf16 v[114:117], v[170:173], v[178:181], v[114:117]
	v_readfirstlane_b32 s9, v21
	v_lshl_add_u64 v[192:193], v[4:5], 0, s[22:23]
	v_readfirstlane_b32 s18, v20
	v_mfma_f32_16x16x32_bf16 v[150:153], v[122:125], v[182:185], v[150:153]
	s_mov_b64 s[20:21], 0x20280
	v_readfirstlane_b32 s19, v18
	v_lshl_add_u64 v[216:217], v[8:9], 0, s[22:23]
	v_mfma_f32_16x16x32_bf16 v[154:157], v[162:165], v[182:185], v[154:157]
	v_lshl_add_u64 v[218:219], v[6:7], 0, s[22:23]
	s_mov_b64 s[22:23], 0x280
	v_mfma_f32_16x16x32_bf16 v[158:161], v[166:169], v[182:185], v[158:161]
	v_mfma_f32_16x16x32_bf16 v[118:121], v[170:173], v[182:185], v[118:121]
	v_mfma_f32_16x16x32_bf16 v[30:33], v[122:125], v[186:189], v[30:33]
	v_mfma_f32_16x16x32_bf16 v[34:37], v[162:165], v[186:189], v[34:37]
	v_mfma_f32_16x16x32_bf16 v[38:41], v[166:169], v[186:189], v[38:41]
	v_mfma_f32_16x16x32_bf16 v[42:45], v[170:173], v[186:189], v[42:45]
	ds_read_b128 v[122:125], v10 offset:16384
	ds_read_b128 v[162:165], v10 offset:17408
	ds_read_b128 v[166:169], v10 offset:18432
	ds_read_b128 v[170:173], v10 offset:19456
	ds_read_b128 v[174:177], v0
	ds_read_b128 v[178:181], v0 offset:1024
	ds_read_b128 v[182:185], v0 offset:2048
	ds_read_b128 v[186:189], v0 offset:3072
	s_waitcnt lgkmcnt(0)
	v_mfma_f32_16x16x32_bf16 v[62:65], v[122:125], v[174:177], v[62:65]
	v_mfma_f32_16x16x32_bf16 v[66:69], v[162:165], v[174:177], v[66:69]
	v_mfma_f32_16x16x32_bf16 v[70:73], v[166:169], v[174:177], v[70:73]
	v_mfma_f32_16x16x32_bf16 v[46:49], v[170:173], v[174:177], v[46:49]
	v_mfma_f32_16x16x32_bf16 v[74:77], v[122:125], v[178:181], v[74:77]
	v_mfma_f32_16x16x32_bf16 v[78:81], v[162:165], v[178:181], v[78:81]
	v_mfma_f32_16x16x32_bf16 v[82:85], v[166:169], v[178:181], v[82:85]
	v_mfma_f32_16x16x32_bf16 v[50:53], v[170:173], v[178:181], v[50:53]
	v_mfma_f32_16x16x32_bf16 v[86:89], v[122:125], v[182:185], v[86:89]
	v_mfma_f32_16x16x32_bf16 v[90:93], v[162:165], v[182:185], v[90:93]
	v_mfma_f32_16x16x32_bf16 v[94:97], v[166:169], v[182:185], v[94:97]
	v_mfma_f32_16x16x32_bf16 v[54:57], v[170:173], v[182:185], v[54:57]
	v_mfma_f32_16x16x32_bf16 v[98:101], v[122:125], v[186:189], v[98:101]
	v_mfma_f32_16x16x32_bf16 v[102:105], v[162:165], v[186:189], v[102:105]
	v_mfma_f32_16x16x32_bf16 v[106:109], v[166:169], v[186:189], v[106:109]
	v_mfma_f32_16x16x32_bf16 v[58:61], v[170:173], v[186:189], v[58:61]
	ds_read_b128 v[174:177], v0 offset:4096
	ds_read_b128 v[178:181], v0 offset:5120
	ds_read_b128 v[182:185], v0 offset:6144
	ds_read_b128 v[186:189], v0 offset:7168
	s_waitcnt vmcnt(6) lgkmcnt(0)
	s_barrier
	global_load_lds_dwordx4 v[190:191], off
	s_mov_b32 m0, s9
	v_lshl_add_u64 v[190:191], v[2:3], 0, s[20:21]
	global_load_lds_dwordx4 v[192:193], off
	s_mov_b32 m0, s18
	s_mov_b64 s[20:21], 0x30280
	global_load_lds_dwordx4 v[194:195], off
	s_mov_b32 m0, s19
	v_lshl_add_u64 v[192:193], v[2:3], 0, s[20:21]
	v_readfirstlane_b32 s21, v28
	global_load_lds_dwordx4 v[214:215], off
	s_mov_b32 m0, s21
	v_readfirstlane_b32 s20, v29
	global_load_lds_dwordx4 v[216:217], off
	s_mov_b32 m0, s20
	s_waitcnt lgkmcnt(0)
	v_mfma_f32_16x16x32_bf16 v[126:129], v[122:125], v[174:177], v[126:129]
	global_load_lds_dwordx4 v[218:219], off
	v_lshl_add_u64 v[194:195], v[8:9], 0, s[22:23]
	v_mfma_f32_16x16x32_bf16 v[130:133], v[162:165], v[174:177], v[130:133]
	v_lshl_add_u64 v[214:215], v[6:7], 0, s[22:23]
	v_mfma_f32_16x16x32_bf16 v[134:137], v[166:169], v[174:177], v[134:137]
	v_mfma_f32_16x16x32_bf16 v[110:113], v[170:173], v[174:177], v[110:113]
	v_mfma_f32_16x16x32_bf16 v[138:141], v[122:125], v[178:181], v[138:141]
	v_mfma_f32_16x16x32_bf16 v[142:145], v[162:165], v[178:181], v[142:145]
	v_mfma_f32_16x16x32_bf16 v[146:149], v[166:169], v[178:181], v[146:149]
	v_mfma_f32_16x16x32_bf16 v[114:117], v[170:173], v[178:181], v[114:117]
	v_mfma_f32_16x16x32_bf16 v[150:153], v[122:125], v[182:185], v[150:153]
	v_mfma_f32_16x16x32_bf16 v[154:157], v[162:165], v[182:185], v[154:157]
	v_mfma_f32_16x16x32_bf16 v[158:161], v[166:169], v[182:185], v[158:161]
	v_mfma_f32_16x16x32_bf16 v[118:121], v[170:173], v[182:185], v[118:121]
	v_mfma_f32_16x16x32_bf16 v[30:33], v[122:125], v[186:189], v[30:33]
	v_mfma_f32_16x16x32_bf16 v[34:37], v[162:165], v[186:189], v[34:37]
	v_mfma_f32_16x16x32_bf16 v[38:41], v[166:169], v[186:189], v[38:41]
	v_mfma_f32_16x16x32_bf16 v[42:45], v[170:173], v[186:189], v[42:45]
	ds_read_b128 v[18:21], v10 offset:40960
	ds_read_b128 v[122:125], v10 offset:41984
	ds_read_b128 v[162:165], v10 offset:43008
	ds_read_b128 v[166:169], v10 offset:44032
	ds_read_b128 v[170:173], v0 offset:24576
	ds_read_b128 v[174:177], v0 offset:25600
	ds_read_b128 v[178:181], v0 offset:26624
	ds_read_b128 v[182:185], v0 offset:27648
	v_lshl_add_u64 v[186:187], v[2:3], 0, s[22:23]
	v_lshl_add_u64 v[188:189], v[4:5], 0, s[22:23]
	v_readfirstlane_b32 s22, v27
	s_waitcnt lgkmcnt(0)
	v_mfma_f32_16x16x32_bf16 v[62:65], v[18:21], v[170:173], v[62:65]
	s_mov_b32 m0, s22
	v_readfirstlane_b32 s23, v26
	v_mfma_f32_16x16x32_bf16 v[66:69], v[122:125], v[170:173], v[66:69]
	v_mfma_f32_16x16x32_bf16 v[70:73], v[162:165], v[170:173], v[70:73]
	v_mfma_f32_16x16x32_bf16 v[46:49], v[166:169], v[170:173], v[46:49]
	v_mfma_f32_16x16x32_bf16 v[74:77], v[18:21], v[174:177], v[74:77]
	v_mfma_f32_16x16x32_bf16 v[78:81], v[122:125], v[174:177], v[78:81]
	v_mfma_f32_16x16x32_bf16 v[82:85], v[162:165], v[174:177], v[82:85]
	v_mfma_f32_16x16x32_bf16 v[50:53], v[166:169], v[174:177], v[50:53]
	v_mfma_f32_16x16x32_bf16 v[86:89], v[18:21], v[178:181], v[86:89]
	v_mfma_f32_16x16x32_bf16 v[90:93], v[122:125], v[178:181], v[90:93]
	v_mfma_f32_16x16x32_bf16 v[94:97], v[162:165], v[178:181], v[94:97]
	v_mfma_f32_16x16x32_bf16 v[54:57], v[166:169], v[178:181], v[54:57]
	v_mfma_f32_16x16x32_bf16 v[98:101], v[18:21], v[182:185], v[98:101]
	v_mfma_f32_16x16x32_bf16 v[102:105], v[122:125], v[182:185], v[102:105]
	v_mfma_f32_16x16x32_bf16 v[106:109], v[162:165], v[182:185], v[106:109]
	v_mfma_f32_16x16x32_bf16 v[58:61], v[166:169], v[182:185], v[58:61]
	ds_read_b128 v[170:173], v0 offset:28672
	ds_read_b128 v[174:177], v0 offset:29696
	ds_read_b128 v[178:181], v0 offset:30720
	ds_read_b128 v[182:185], v0 offset:31744
	s_waitcnt vmcnt(6) lgkmcnt(0)
	s_barrier
	global_load_lds_dwordx4 v[186:187], off
	s_mov_b32 m0, s23
	v_lshl_add_u64 v[186:187], v[2:3], 0, s[26:27]
	global_load_lds_dwordx4 v[188:189], off
	s_mov_b32 m0, s24
	s_mov_b64 s[26:27], 0x302c0
	global_load_lds_dwordx4 v[190:191], off
	s_mov_b32 m0, s25
	v_lshl_add_u64 v[188:189], v[2:3], 0, s[26:27]
	v_readfirstlane_b32 s26, v23
	global_load_lds_dwordx4 v[192:193], off
	s_mov_b32 m0, s26
	v_readfirstlane_b32 s27, v24
	global_load_lds_dwordx4 v[194:195], off
	s_mov_b32 m0, s27
	s_waitcnt lgkmcnt(0)
	v_mfma_f32_16x16x32_bf16 v[126:129], v[18:21], v[170:173], v[126:129]
	global_load_lds_dwordx4 v[214:215], off
	v_lshl_add_u64 v[190:191], v[8:9], 0, s[36:37]
	v_mfma_f32_16x16x32_bf16 v[130:133], v[122:125], v[170:173], v[130:133]
	v_lshl_add_u64 v[192:193], v[6:7], 0, s[36:37]
	v_mfma_f32_16x16x32_bf16 v[134:137], v[162:165], v[170:173], v[134:137]
	v_mfma_f32_16x16x32_bf16 v[110:113], v[166:169], v[170:173], v[110:113]
	v_mfma_f32_16x16x32_bf16 v[138:141], v[18:21], v[174:177], v[138:141]
	v_mfma_f32_16x16x32_bf16 v[142:145], v[122:125], v[174:177], v[142:145]
	v_mfma_f32_16x16x32_bf16 v[146:149], v[162:165], v[174:177], v[146:149]
	v_mfma_f32_16x16x32_bf16 v[114:117], v[166:169], v[174:177], v[114:117]
	v_mfma_f32_16x16x32_bf16 v[150:153], v[18:21], v[178:181], v[150:153]
	v_mfma_f32_16x16x32_bf16 v[154:157], v[122:125], v[178:181], v[154:157]
	v_mfma_f32_16x16x32_bf16 v[158:161], v[162:165], v[178:181], v[158:161]
	v_mfma_f32_16x16x32_bf16 v[118:121], v[166:169], v[178:181], v[118:121]
	v_mfma_f32_16x16x32_bf16 v[18:21], v[18:21], v[182:185], v[30:33]
	v_mfma_f32_16x16x32_bf16 v[28:31], v[122:125], v[182:185], v[34:37]
	v_mfma_f32_16x16x32_bf16 v[32:35], v[162:165], v[182:185], v[38:41]
	v_mfma_f32_16x16x32_bf16 v[36:39], v[166:169], v[182:185], v[42:45]
	ds_read_b128 v[22:25], v11 offset:16384
	s_nop 1
	ds_read_b128 v[40:43], v11 offset:17408
	ds_read_b128 v[122:125], v11 offset:18432
	ds_read_b128 v[162:165], v11 offset:19456
	ds_read_b128 v[166:169], v0 offset:49152
	ds_read_b128 v[170:173], v0 offset:50176
	ds_read_b128 v[174:177], v0 offset:51200
	ds_read_b128 v[178:181], v0 offset:52224
	v_lshl_add_u64 v[182:183], v[2:3], 0, s[36:37]
	v_lshl_add_u64 v[184:185], v[4:5], 0, s[36:37]
	v_readfirstlane_b32 s36, v12
	s_waitcnt lgkmcnt(0)
	v_mfma_f32_16x16x32_bf16 v[62:65], v[22:25], v[166:169], v[62:65]
	s_mov_b32 m0, s36
	v_readfirstlane_b32 s37, v13
	v_mfma_f32_16x16x32_bf16 v[66:69], v[40:43], v[166:169], v[66:69]
	v_mfma_f32_16x16x32_bf16 v[70:73], v[122:125], v[166:169], v[70:73]
	v_mfma_f32_16x16x32_bf16 v[44:47], v[162:165], v[166:169], v[46:49]
	v_mfma_f32_16x16x32_bf16 v[74:77], v[22:25], v[170:173], v[74:77]
	v_mfma_f32_16x16x32_bf16 v[78:81], v[40:43], v[170:173], v[78:81]
	v_mfma_f32_16x16x32_bf16 v[82:85], v[122:125], v[170:173], v[82:85]
	v_mfma_f32_16x16x32_bf16 v[48:51], v[162:165], v[170:173], v[50:53]
	v_mfma_f32_16x16x32_bf16 v[86:89], v[22:25], v[174:177], v[86:89]
	v_mfma_f32_16x16x32_bf16 v[90:93], v[40:43], v[174:177], v[90:93]
	v_mfma_f32_16x16x32_bf16 v[94:97], v[122:125], v[174:177], v[94:97]
	v_mfma_f32_16x16x32_bf16 v[52:55], v[162:165], v[174:177], v[54:57]
	v_mfma_f32_16x16x32_bf16 v[98:101], v[22:25], v[178:181], v[98:101]
	v_mfma_f32_16x16x32_bf16 v[102:105], v[40:43], v[178:181], v[102:105]
	v_mfma_f32_16x16x32_bf16 v[106:109], v[122:125], v[178:181], v[106:109]
	v_mfma_f32_16x16x32_bf16 v[56:59], v[162:165], v[178:181], v[58:61]
	ds_read_b128 v[166:169], v0 offset:53248
	ds_read_b128 v[170:173], v0 offset:54272
	ds_read_b128 v[174:177], v0 offset:55296
	ds_read_b128 v[178:181], v0 offset:56320
	s_waitcnt vmcnt(6) lgkmcnt(0)
	s_barrier
	global_load_lds_dwordx4 v[182:183], off
	s_mov_b32 m0, s37
	v_lshl_add_u64 v[182:183], v[2:3], 0, s[40:41]
	global_load_lds_dwordx4 v[184:185], off
	s_mov_b32 m0, s38
	s_mov_b64 s[40:41], 0x30300
	global_load_lds_dwordx4 v[186:187], off
	s_mov_b32 m0, s39
	v_lshl_add_u64 v[184:185], v[2:3], 0, s[40:41]
	v_readfirstlane_b32 s40, v16
	global_load_lds_dwordx4 v[188:189], off
	s_mov_b32 m0, s40
	v_readfirstlane_b32 s41, v17
	global_load_lds_dwordx4 v[190:191], off
	s_mov_b32 m0, s41
	s_waitcnt lgkmcnt(0)
	v_mfma_f32_16x16x32_bf16 v[126:129], v[22:25], v[166:169], v[126:129]
	global_load_lds_dwordx4 v[192:193], off
	s_mov_b32 m0, s8
	v_mfma_f32_16x16x32_bf16 v[130:133], v[40:43], v[166:169], v[130:133]
	v_lshl_add_u64 v[186:187], v[8:9], 0, s[42:43]
	v_lshl_add_u64 v[188:189], v[6:7], 0, s[42:43]
	v_mfma_f32_16x16x32_bf16 v[134:137], v[122:125], v[166:169], v[134:137]
	v_mfma_f32_16x16x32_bf16 v[110:113], v[162:165], v[166:169], v[110:113]
	v_mfma_f32_16x16x32_bf16 v[138:141], v[22:25], v[170:173], v[138:141]
	v_mfma_f32_16x16x32_bf16 v[142:145], v[40:43], v[170:173], v[142:145]
	v_mfma_f32_16x16x32_bf16 v[146:149], v[122:125], v[170:173], v[146:149]
	v_mfma_f32_16x16x32_bf16 v[114:117], v[162:165], v[170:173], v[114:117]
	v_mfma_f32_16x16x32_bf16 v[150:153], v[22:25], v[174:177], v[150:153]
	v_mfma_f32_16x16x32_bf16 v[154:157], v[40:43], v[174:177], v[154:157]
	v_mfma_f32_16x16x32_bf16 v[158:161], v[122:125], v[174:177], v[158:161]
	v_mfma_f32_16x16x32_bf16 v[118:121], v[162:165], v[174:177], v[118:121]
	v_mfma_f32_16x16x32_bf16 v[18:21], v[22:25], v[178:181], v[18:21]
	v_mfma_f32_16x16x32_bf16 v[22:25], v[40:43], v[178:181], v[28:31]
	v_mfma_f32_16x16x32_bf16 v[26:29], v[122:125], v[178:181], v[32:35]
	v_mfma_f32_16x16x32_bf16 v[30:33], v[162:165], v[178:181], v[36:39]
	ds_read_b128 v[12:15], v10 offset:16384
	s_nop 1
	ds_read_b128 v[34:37], v10 offset:17408
	ds_read_b128 v[38:41], v10 offset:18432
	ds_read_b128 v[122:125], v10 offset:19456
	ds_read_b128 v[162:165], v0
	ds_read_b128 v[166:169], v0 offset:1024
	ds_read_b128 v[170:173], v0 offset:2048
	ds_read_b128 v[174:177], v0 offset:3072
	v_lshl_add_u64 v[178:179], v[2:3], 0, s[42:43]
	v_lshl_add_u64 v[180:181], v[4:5], 0, s[42:43]
	s_waitcnt lgkmcnt(0)
	v_mfma_f32_16x16x32_bf16 v[60:63], v[12:15], v[162:165], v[62:65]
	s_mov_b64 s[42:43], 0x20340
	v_mfma_f32_16x16x32_bf16 v[64:67], v[34:37], v[162:165], v[66:69]
	v_mfma_f32_16x16x32_bf16 v[68:71], v[38:41], v[162:165], v[70:73]
	v_mfma_f32_16x16x32_bf16 v[42:45], v[122:125], v[162:165], v[44:47]
	v_mfma_f32_16x16x32_bf16 v[72:75], v[12:15], v[166:169], v[74:77]
	v_mfma_f32_16x16x32_bf16 v[76:79], v[34:37], v[166:169], v[78:81]
	v_mfma_f32_16x16x32_bf16 v[80:83], v[38:41], v[166:169], v[82:85]
	v_mfma_f32_16x16x32_bf16 v[46:49], v[122:125], v[166:169], v[48:51]
	v_mfma_f32_16x16x32_bf16 v[84:87], v[12:15], v[170:173], v[86:89]
	v_mfma_f32_16x16x32_bf16 v[88:91], v[34:37], v[170:173], v[90:93]
	v_mfma_f32_16x16x32_bf16 v[92:95], v[38:41], v[170:173], v[94:97]
	v_mfma_f32_16x16x32_bf16 v[50:53], v[122:125], v[170:173], v[52:55]
	v_mfma_f32_16x16x32_bf16 v[96:99], v[12:15], v[174:177], v[98:101]
	v_mfma_f32_16x16x32_bf16 v[100:103], v[34:37], v[174:177], v[102:105]
	v_mfma_f32_16x16x32_bf16 v[104:107], v[38:41], v[174:177], v[106:109]
	v_mfma_f32_16x16x32_bf16 v[54:57], v[122:125], v[174:177], v[56:59]
	ds_read_b128 v[162:165], v0 offset:4096
	ds_read_b128 v[166:169], v0 offset:5120
	ds_read_b128 v[170:173], v0 offset:6144
	ds_read_b128 v[174:177], v0 offset:7168
	s_waitcnt vmcnt(6) lgkmcnt(0)
	s_barrier
	global_load_lds_dwordx4 v[178:179], off
	s_mov_b32 m0, s9
	s_waitcnt lgkmcnt(0)
	v_mfma_f32_16x16x32_bf16 v[126:129], v[12:15], v[162:165], v[126:129]
	global_load_lds_dwordx4 v[180:181], off
	s_mov_b32 m0, s18
	v_mfma_f32_16x16x32_bf16 v[130:133], v[34:37], v[162:165], v[130:133]
	global_load_lds_dwordx4 v[182:183], off
	s_mov_b32 m0, s19
	v_mfma_f32_16x16x32_bf16 v[134:137], v[38:41], v[162:165], v[134:137]
	global_load_lds_dwordx4 v[184:185], off
	s_mov_b32 m0, s21
	v_mfma_f32_16x16x32_bf16 v[108:111], v[122:125], v[162:165], v[110:113]
	global_load_lds_dwordx4 v[186:187], off
	s_mov_b32 m0, s20
	v_mfma_f32_16x16x32_bf16 v[138:141], v[12:15], v[166:169], v[138:141]
	global_load_lds_dwordx4 v[188:189], off
	v_lshl_add_u64 v[178:179], v[2:3], 0, s[58:59]
	v_mfma_f32_16x16x32_bf16 v[142:145], v[34:37], v[166:169], v[142:145]
	s_mov_b32 m0, s22
	v_lshl_add_u64 v[180:181], v[4:5], 0, s[58:59]
	v_lshl_add_u64 v[182:183], v[2:3], 0, s[42:43]
	v_mfma_f32_16x16x32_bf16 v[146:149], v[38:41], v[166:169], v[146:149]
	s_mov_b64 s[42:43], 0x30340
	v_lshl_add_u64 v[184:185], v[2:3], 0, s[42:43]
	v_lshl_add_u64 v[186:187], v[8:9], 0, s[58:59]
	v_mfma_f32_16x16x32_bf16 v[112:115], v[122:125], v[166:169], v[114:117]
	v_lshl_add_u64 v[188:189], v[6:7], 0, s[58:59]
	s_mov_b64 s[58:59], 0x380
	v_mfma_f32_16x16x32_bf16 v[150:153], v[12:15], v[170:173], v[150:153]
	v_mfma_f32_16x16x32_bf16 v[154:157], v[34:37], v[170:173], v[154:157]
	v_mfma_f32_16x16x32_bf16 v[158:161], v[38:41], v[170:173], v[158:161]
	v_mfma_f32_16x16x32_bf16 v[116:119], v[122:125], v[170:173], v[118:121]
	v_mfma_f32_16x16x32_bf16 v[12:15], v[12:15], v[174:177], v[18:21]
	v_mfma_f32_16x16x32_bf16 v[16:19], v[34:37], v[174:177], v[22:25]
	v_mfma_f32_16x16x32_bf16 v[20:23], v[38:41], v[174:177], v[26:29]
	v_mfma_f32_16x16x32_bf16 v[24:27], v[122:125], v[174:177], v[30:33]
	s_nop 2
	ds_read_b128 v[28:31], v10 offset:40960
	ds_read_b128 v[32:35], v10 offset:41984
	ds_read_b128 v[36:39], v10 offset:43008
	ds_read_b128 v[120:123], v10 offset:44032
	ds_read_b128 v[162:165], v0 offset:24576
	ds_read_b128 v[166:169], v0 offset:25600
	ds_read_b128 v[170:173], v0 offset:26624
	ds_read_b128 v[174:177], v0 offset:27648
	s_waitcnt lgkmcnt(0)
	v_mfma_f32_16x16x32_bf16 v[58:61], v[28:31], v[162:165], v[60:63]
	v_mfma_f32_16x16x32_bf16 v[62:65], v[32:35], v[162:165], v[64:67]
	v_mfma_f32_16x16x32_bf16 v[66:69], v[36:39], v[162:165], v[68:71]
	v_mfma_f32_16x16x32_bf16 v[40:43], v[120:123], v[162:165], v[42:45]
	v_mfma_f32_16x16x32_bf16 v[70:73], v[28:31], v[166:169], v[72:75]
	v_mfma_f32_16x16x32_bf16 v[74:77], v[32:35], v[166:169], v[76:79]
	v_mfma_f32_16x16x32_bf16 v[78:81], v[36:39], v[166:169], v[80:83]
	v_mfma_f32_16x16x32_bf16 v[44:47], v[120:123], v[166:169], v[46:49]
	v_mfma_f32_16x16x32_bf16 v[82:85], v[28:31], v[170:173], v[84:87]
	v_mfma_f32_16x16x32_bf16 v[86:89], v[32:35], v[170:173], v[88:91]
	v_mfma_f32_16x16x32_bf16 v[90:93], v[36:39], v[170:173], v[92:95]
	v_mfma_f32_16x16x32_bf16 v[48:51], v[120:123], v[170:173], v[50:53]
	v_mfma_f32_16x16x32_bf16 v[94:97], v[28:31], v[174:177], v[96:99]
	v_mfma_f32_16x16x32_bf16 v[98:101], v[32:35], v[174:177], v[100:103]
	v_mfma_f32_16x16x32_bf16 v[102:105], v[36:39], v[174:177], v[104:107]
	v_mfma_f32_16x16x32_bf16 v[52:55], v[120:123], v[174:177], v[54:57]
	ds_read_b128 v[162:165], v0 offset:28672
	ds_read_b128 v[166:169], v0 offset:29696
	ds_read_b128 v[170:173], v0 offset:30720
	ds_read_b128 v[174:177], v0 offset:31744
	s_waitcnt vmcnt(6) lgkmcnt(0)
	s_barrier
	global_load_lds_dwordx4 v[178:179], off
	s_mov_b32 m0, s23
	s_waitcnt lgkmcnt(0)
	v_mfma_f32_16x16x32_bf16 v[124:127], v[28:31], v[162:165], v[126:129]
	global_load_lds_dwordx4 v[180:181], off
	s_mov_b32 m0, s24
	v_mfma_f32_16x16x32_bf16 v[128:131], v[32:35], v[162:165], v[130:133]
	global_load_lds_dwordx4 v[182:183], off
	s_mov_b32 m0, s25
	v_mfma_f32_16x16x32_bf16 v[132:135], v[36:39], v[162:165], v[134:137]
	global_load_lds_dwordx4 v[184:185], off
	s_mov_b32 m0, s26
	v_mfma_f32_16x16x32_bf16 v[106:109], v[120:123], v[162:165], v[108:111]
	global_load_lds_dwordx4 v[186:187], off
	s_mov_b32 m0, s27
	v_mfma_f32_16x16x32_bf16 v[136:139], v[28:31], v[166:169], v[138:141]
	global_load_lds_dwordx4 v[188:189], off
	s_mov_b32 m0, s36
	v_mfma_f32_16x16x32_bf16 v[140:143], v[32:35], v[166:169], v[142:145]
	v_lshl_add_u64 v[178:179], v[4:5], 0, s[58:59]
	s_mov_b64 s[22:23], 0x20380
	v_lshl_add_u64 v[180:181], v[2:3], 0, s[22:23]
	v_mfma_f32_16x16x32_bf16 v[144:147], v[36:39], v[166:169], v[146:149]
	s_mov_b64 s[22:23], 0x30380
	v_lshl_add_u64 v[182:183], v[2:3], 0, s[22:23]
	v_lshl_add_u64 v[184:185], v[8:9], 0, s[58:59]
	v_mfma_f32_16x16x32_bf16 v[110:113], v[120:123], v[166:169], v[112:115]
	v_lshl_add_u64 v[186:187], v[6:7], 0, s[58:59]
	s_mov_b64 s[22:23], 0x203c0
	s_mov_b64 s[26:27], 0x3c0
	v_mfma_f32_16x16x32_bf16 v[148:151], v[28:31], v[170:173], v[150:153]
	s_mov_b64 s[24:25], 0x3000
	v_mfma_f32_16x16x32_bf16 v[152:155], v[32:35], v[170:173], v[154:157]
	v_mfma_f32_16x16x32_bf16 v[156:159], v[36:39], v[170:173], v[158:161]
	v_mfma_f32_16x16x32_bf16 v[114:117], v[120:123], v[170:173], v[116:119]
	v_mfma_f32_16x16x32_bf16 v[12:15], v[28:31], v[174:177], v[12:15]
	v_mfma_f32_16x16x32_bf16 v[16:19], v[32:35], v[174:177], v[16:19]
	v_mfma_f32_16x16x32_bf16 v[20:23], v[36:39], v[174:177], v[20:23]
	v_mfma_f32_16x16x32_bf16 v[24:27], v[120:123], v[174:177], v[24:27]
	ds_read_b128 v[28:31], v11 offset:16384
	ds_read_b128 v[32:35], v11 offset:17408
	ds_read_b128 v[36:39], v11 offset:18432
	ds_read_b128 v[118:121], v11 offset:19456
	ds_read_b128 v[160:163], v0 offset:49152
	ds_read_b128 v[164:167], v0 offset:50176
	ds_read_b128 v[168:171], v0 offset:51200
	ds_read_b128 v[172:175], v0 offset:52224
	v_lshl_add_u64 v[176:177], v[2:3], 0, s[58:59]
	s_mov_b32 s59, s44
	s_waitcnt lgkmcnt(0)
	v_mfma_f32_16x16x32_bf16 v[56:59], v[28:31], v[160:163], v[58:61]
	v_mfma_f32_16x16x32_bf16 v[60:63], v[32:35], v[160:163], v[62:65]
	v_mfma_f32_16x16x32_bf16 v[64:67], v[36:39], v[160:163], v[66:69]
	v_mfma_f32_16x16x32_bf16 v[40:43], v[118:121], v[160:163], v[40:43]
	v_mfma_f32_16x16x32_bf16 v[68:71], v[28:31], v[164:167], v[70:73]
	v_mfma_f32_16x16x32_bf16 v[72:75], v[32:35], v[164:167], v[74:77]
	v_mfma_f32_16x16x32_bf16 v[76:79], v[36:39], v[164:167], v[78:81]
	v_mfma_f32_16x16x32_bf16 v[44:47], v[118:121], v[164:167], v[44:47]
	v_mfma_f32_16x16x32_bf16 v[80:83], v[28:31], v[168:171], v[82:85]
	v_mfma_f32_16x16x32_bf16 v[84:87], v[32:35], v[168:171], v[86:89]
	v_mfma_f32_16x16x32_bf16 v[88:91], v[36:39], v[168:171], v[90:93]
	v_mfma_f32_16x16x32_bf16 v[48:51], v[118:121], v[168:171], v[48:51]
	v_mfma_f32_16x16x32_bf16 v[92:95], v[28:31], v[172:175], v[94:97]
	v_mfma_f32_16x16x32_bf16 v[96:99], v[32:35], v[172:175], v[98:101]
	v_mfma_f32_16x16x32_bf16 v[100:103], v[36:39], v[172:175], v[102:105]
	v_mfma_f32_16x16x32_bf16 v[52:55], v[118:121], v[172:175], v[52:55]
	ds_read_b128 v[160:163], v0 offset:53248
	ds_read_b128 v[164:167], v0 offset:54272
	ds_read_b128 v[168:171], v0 offset:55296
	ds_read_b128 v[172:175], v0 offset:56320
	s_waitcnt vmcnt(6) lgkmcnt(0)
	s_barrier
	global_load_lds_dwordx4 v[176:177], off
	s_mov_b32 m0, s37
	s_waitcnt lgkmcnt(0)
	v_mfma_f32_16x16x32_bf16 v[122:125], v[28:31], v[160:163], v[124:127]
	global_load_lds_dwordx4 v[178:179], off
	s_mov_b32 m0, s38
	v_mfma_f32_16x16x32_bf16 v[126:129], v[32:35], v[160:163], v[128:131]
	global_load_lds_dwordx4 v[180:181], off
	s_mov_b32 m0, s39
	v_mfma_f32_16x16x32_bf16 v[130:133], v[36:39], v[160:163], v[132:135]
	global_load_lds_dwordx4 v[182:183], off
	s_mov_b32 m0, s40
	v_mfma_f32_16x16x32_bf16 v[104:107], v[118:121], v[160:163], v[106:109]
	global_load_lds_dwordx4 v[184:185], off
	s_mov_b32 m0, s41
	v_mfma_f32_16x16x32_bf16 v[134:137], v[28:31], v[164:167], v[136:139]
	global_load_lds_dwordx4 v[186:187], off
	v_lshl_add_u64 v[176:177], v[6:7], 0, s[26:27]
	v_mfma_f32_16x16x32_bf16 v[138:141], v[32:35], v[164:167], v[140:143]
	s_mov_b32 m0, s8
	v_mfma_f32_16x16x32_bf16 v[142:145], v[36:39], v[164:167], v[144:147]
	v_mfma_f32_16x16x32_bf16 v[108:111], v[118:121], v[164:167], v[110:113]
	v_lshl_add_u64 v[166:167], v[2:3], 0, s[26:27]
	v_mfma_f32_16x16x32_bf16 v[146:149], v[28:31], v[168:171], v[148:151]
	v_mfma_f32_16x16x32_bf16 v[150:153], v[32:35], v[168:171], v[152:155]
	v_mfma_f32_16x16x32_bf16 v[154:157], v[36:39], v[168:171], v[156:159]
	v_mfma_f32_16x16x32_bf16 v[112:115], v[118:121], v[168:171], v[114:117]
	v_lshl_add_u64 v[170:171], v[2:3], 0, s[22:23]
	s_mov_b64 s[22:23], 0x303c0
	v_lshl_add_u64 v[168:169], v[4:5], 0, s[26:27]
	v_mfma_f32_16x16x32_bf16 v[12:15], v[28:31], v[172:175], v[12:15]
	v_mfma_f32_16x16x32_bf16 v[16:19], v[32:35], v[172:175], v[16:19]
	v_mfma_f32_16x16x32_bf16 v[20:23], v[36:39], v[172:175], v[20:23]
	v_mfma_f32_16x16x32_bf16 v[24:27], v[118:121], v[172:175], v[24:27]
	v_lshl_add_u64 v[172:173], v[2:3], 0, s[22:23]
	v_lshl_add_u64 v[174:175], v[8:9], 0, s[26:27]
	ds_read_b128 v[2:5], v10 offset:16384
	ds_read_b128 v[6:9], v10 offset:17408
	ds_read_b128 v[28:31], v10 offset:18432
	ds_read_b128 v[32:35], v10 offset:19456
	ds_read_b128 v[36:39], v0
	ds_read_b128 v[116:119], v0 offset:1024
	ds_read_b128 v[158:161], v0 offset:2048
	ds_read_b128 v[162:165], v0 offset:3072
	s_waitcnt lgkmcnt(0)
	v_mfma_f32_16x16x32_bf16 v[56:59], v[2:5], v[36:39], v[56:59]
	v_mfma_f32_16x16x32_bf16 v[60:63], v[6:9], v[36:39], v[60:63]
	v_mfma_f32_16x16x32_bf16 v[64:67], v[28:31], v[36:39], v[64:67]
	v_mfma_f32_16x16x32_bf16 v[36:39], v[32:35], v[36:39], v[40:43]
	v_mfma_f32_16x16x32_bf16 v[40:43], v[2:5], v[116:119], v[68:71]
	v_mfma_f32_16x16x32_bf16 v[68:71], v[6:9], v[116:119], v[72:75]
	v_mfma_f32_16x16x32_bf16 v[72:75], v[28:31], v[116:119], v[76:79]
	v_mfma_f32_16x16x32_bf16 v[44:47], v[32:35], v[116:119], v[44:47]
	v_mfma_f32_16x16x32_bf16 v[76:79], v[2:5], v[158:161], v[80:83]
	v_mfma_f32_16x16x32_bf16 v[80:83], v[6:9], v[158:161], v[84:87]
	v_mfma_f32_16x16x32_bf16 v[84:87], v[28:31], v[158:161], v[88:91]
	v_mfma_f32_16x16x32_bf16 v[48:51], v[32:35], v[158:161], v[48:51]
	v_mfma_f32_16x16x32_bf16 v[88:91], v[2:5], v[162:165], v[92:95]
	v_mfma_f32_16x16x32_bf16 v[92:95], v[6:9], v[162:165], v[96:99]
	v_mfma_f32_16x16x32_bf16 v[96:99], v[28:31], v[162:165], v[100:103]
	v_mfma_f32_16x16x32_bf16 v[52:55], v[32:35], v[162:165], v[52:55]
	s_nop 1
	ds_read_b128 v[100:103], v0 offset:4096
	ds_read_b128 v[116:119], v0 offset:5120
	ds_read_b128 v[158:161], v0 offset:6144
	ds_read_b128 v[162:165], v0 offset:7168
	s_waitcnt vmcnt(6) lgkmcnt(0)
	s_barrier
	global_load_lds_dwordx4 v[166:167], off
	s_mov_b32 m0, s9
	s_waitcnt lgkmcnt(0)
	v_mfma_f32_16x16x32_bf16 v[120:123], v[2:5], v[100:103], v[122:125]
	global_load_lds_dwordx4 v[168:169], off
	s_mov_b32 m0, s18
	v_mfma_f32_16x16x32_bf16 v[124:127], v[6:9], v[100:103], v[126:129]
	global_load_lds_dwordx4 v[170:171], off
	s_mov_b32 m0, s19
	v_mfma_f32_16x16x32_bf16 v[128:131], v[28:31], v[100:103], v[130:133]
	global_load_lds_dwordx4 v[172:173], off
	s_mov_b32 m0, s21
	v_mfma_f32_16x16x32_bf16 v[100:103], v[32:35], v[100:103], v[104:107]
	global_load_lds_dwordx4 v[174:175], off
	s_mov_b32 m0, s20
	v_mfma_f32_16x16x32_bf16 v[104:107], v[2:5], v[116:119], v[134:137]
	global_load_lds_dwordx4 v[176:177], off
	v_mfma_f32_16x16x32_bf16 v[132:135], v[6:9], v[116:119], v[138:141]
	v_mfma_f32_16x16x32_bf16 v[136:139], v[28:31], v[116:119], v[142:145]
	v_mfma_f32_16x16x32_bf16 v[108:111], v[32:35], v[116:119], v[108:111]
	v_mfma_f32_16x16x32_bf16 v[116:119], v[2:5], v[158:161], v[146:149]
	v_mfma_f32_16x16x32_bf16 v[140:143], v[6:9], v[158:161], v[150:153]
	v_mfma_f32_16x16x32_bf16 v[144:147], v[28:31], v[158:161], v[154:157]
	v_mfma_f32_16x16x32_bf16 v[112:115], v[32:35], v[158:161], v[112:115]
	v_mfma_f32_16x16x32_bf16 v[2:5], v[2:5], v[162:165], v[12:15]
	v_mfma_f32_16x16x32_bf16 v[6:9], v[6:9], v[162:165], v[16:19]
	v_mfma_f32_16x16x32_bf16 v[12:15], v[28:31], v[162:165], v[20:23]
	v_mfma_f32_16x16x32_bf16 v[16:19], v[32:35], v[162:165], v[24:27]
	s_nop 1
	ds_read_b128 v[20:23], v10 offset:40960
	ds_read_b128 v[24:27], v10 offset:41984
	ds_read_b128 v[28:31], v10 offset:43008
	ds_read_b128 v[32:35], v10 offset:44032
	ds_read_b128 v[148:151], v0 offset:24576
	ds_read_b128 v[152:155], v0 offset:25600
	ds_read_b128 v[156:159], v0 offset:26624
	ds_read_b128 v[160:163], v0 offset:27648
	s_waitcnt lgkmcnt(0)
	v_mfma_f32_16x16x32_bf16 v[56:59], v[20:23], v[148:151], v[56:59]
	v_mfma_f32_16x16x32_bf16 v[60:63], v[24:27], v[148:151], v[60:63]
	v_mfma_f32_16x16x32_bf16 v[64:67], v[28:31], v[148:151], v[64:67]
	v_mfma_f32_16x16x32_bf16 v[36:39], v[32:35], v[148:151], v[36:39]
	v_mfma_f32_16x16x32_bf16 v[40:43], v[20:23], v[152:155], v[40:43]
	v_mfma_f32_16x16x32_bf16 v[68:71], v[24:27], v[152:155], v[68:71]
	v_mfma_f32_16x16x32_bf16 v[72:75], v[28:31], v[152:155], v[72:75]
	v_mfma_f32_16x16x32_bf16 v[44:47], v[32:35], v[152:155], v[44:47]
	v_mfma_f32_16x16x32_bf16 v[76:79], v[20:23], v[156:159], v[76:79]
	v_mfma_f32_16x16x32_bf16 v[80:83], v[24:27], v[156:159], v[80:83]
	v_mfma_f32_16x16x32_bf16 v[84:87], v[28:31], v[156:159], v[84:87]
	v_mfma_f32_16x16x32_bf16 v[48:51], v[32:35], v[156:159], v[48:51]
	v_mfma_f32_16x16x32_bf16 v[88:91], v[20:23], v[160:163], v[88:91]
	v_mfma_f32_16x16x32_bf16 v[92:95], v[24:27], v[160:163], v[92:95]
	v_mfma_f32_16x16x32_bf16 v[96:99], v[28:31], v[160:163], v[96:99]
	v_mfma_f32_16x16x32_bf16 v[52:55], v[32:35], v[160:163], v[52:55]
	ds_read_b128 v[148:151], v0 offset:28672
	ds_read_b128 v[152:155], v0 offset:29696
	ds_read_b128 v[156:159], v0 offset:30720
	ds_read_b128 v[160:163], v0 offset:31744
	s_waitcnt vmcnt(6) lgkmcnt(0)
	s_barrier
	s_waitcnt lgkmcnt(0)
	v_mfma_f32_16x16x32_bf16 v[120:123], v[20:23], v[148:151], v[120:123]
	v_mfma_f32_16x16x32_bf16 v[124:127], v[24:27], v[148:151], v[124:127]
	v_mfma_f32_16x16x32_bf16 v[128:131], v[28:31], v[148:151], v[128:131]
	v_mfma_f32_16x16x32_bf16 v[100:103], v[32:35], v[148:151], v[100:103]
	v_mfma_f32_16x16x32_bf16 v[104:107], v[20:23], v[152:155], v[104:107]
	v_mfma_f32_16x16x32_bf16 v[132:135], v[24:27], v[152:155], v[132:135]
	v_mfma_f32_16x16x32_bf16 v[136:139], v[28:31], v[152:155], v[136:139]
	v_mfma_f32_16x16x32_bf16 v[108:111], v[32:35], v[152:155], v[108:111]
	v_mfma_f32_16x16x32_bf16 v[116:119], v[20:23], v[156:159], v[116:119]
	v_mfma_f32_16x16x32_bf16 v[140:143], v[24:27], v[156:159], v[140:143]
	v_mfma_f32_16x16x32_bf16 v[144:147], v[28:31], v[156:159], v[144:147]
	v_mfma_f32_16x16x32_bf16 v[112:115], v[32:35], v[156:159], v[112:115]
	v_mfma_f32_16x16x32_bf16 v[2:5], v[20:23], v[160:163], v[2:5]
	v_mfma_f32_16x16x32_bf16 v[6:9], v[24:27], v[160:163], v[6:9]
	v_mfma_f32_16x16x32_bf16 v[12:15], v[28:31], v[160:163], v[12:15]
	v_mfma_f32_16x16x32_bf16 v[16:19], v[32:35], v[160:163], v[16:19]
	ds_read_b128 v[20:23], v11 offset:16384
	ds_read_b128 v[24:27], v11 offset:17408
	ds_read_b128 v[28:31], v11 offset:18432
	ds_read_b128 v[32:35], v11 offset:19456
	ds_read_b128 v[148:151], v0 offset:49152
	ds_read_b128 v[152:155], v0 offset:50176
	ds_read_b128 v[156:159], v0 offset:51200
	ds_read_b128 v[160:163], v0 offset:52224
	s_waitcnt lgkmcnt(0)
	v_mfma_f32_16x16x32_bf16 v[56:59], v[20:23], v[148:151], v[56:59]
	v_mfma_f32_16x16x32_bf16 v[60:63], v[24:27], v[148:151], v[60:63]
	v_mfma_f32_16x16x32_bf16 v[64:67], v[28:31], v[148:151], v[64:67]
	v_mfma_f32_16x16x32_bf16 v[36:39], v[32:35], v[148:151], v[36:39]
	v_mfma_f32_16x16x32_bf16 v[40:43], v[20:23], v[152:155], v[40:43]
	v_mfma_f32_16x16x32_bf16 v[68:71], v[24:27], v[152:155], v[68:71]
	v_mfma_f32_16x16x32_bf16 v[72:75], v[28:31], v[152:155], v[72:75]
	v_mfma_f32_16x16x32_bf16 v[44:47], v[32:35], v[152:155], v[44:47]
	v_mfma_f32_16x16x32_bf16 v[76:79], v[20:23], v[156:159], v[76:79]
	v_mfma_f32_16x16x32_bf16 v[80:83], v[24:27], v[156:159], v[80:83]
	v_mfma_f32_16x16x32_bf16 v[84:87], v[28:31], v[156:159], v[84:87]
	v_mfma_f32_16x16x32_bf16 v[48:51], v[32:35], v[156:159], v[48:51]
	v_mfma_f32_16x16x32_bf16 v[88:91], v[20:23], v[160:163], v[88:91]
	v_mfma_f32_16x16x32_bf16 v[92:95], v[24:27], v[160:163], v[92:95]
	v_mfma_f32_16x16x32_bf16 v[96:99], v[28:31], v[160:163], v[96:99]
	v_mfma_f32_16x16x32_bf16 v[52:55], v[32:35], v[160:163], v[52:55]
	ds_read_b128 v[148:151], v0 offset:53248
	ds_read_b128 v[152:155], v0 offset:54272
	ds_read_b128 v[156:159], v0 offset:55296
	ds_read_b128 v[160:163], v0 offset:56320
	s_waitcnt vmcnt(0) lgkmcnt(0)
	s_barrier
	s_waitcnt lgkmcnt(0)
	v_mfma_f32_16x16x32_bf16 v[120:123], v[20:23], v[148:151], v[120:123]
	v_mfma_f32_16x16x32_bf16 v[124:127], v[24:27], v[148:151], v[124:127]
	v_mfma_f32_16x16x32_bf16 v[128:131], v[28:31], v[148:151], v[128:131]
	v_mfma_f32_16x16x32_bf16 v[100:103], v[32:35], v[148:151], v[100:103]
	v_mfma_f32_16x16x32_bf16 v[104:107], v[20:23], v[152:155], v[104:107]
	v_mfma_f32_16x16x32_bf16 v[132:135], v[24:27], v[152:155], v[132:135]
	v_mfma_f32_16x16x32_bf16 v[136:139], v[28:31], v[152:155], v[136:139]
	v_mfma_f32_16x16x32_bf16 v[108:111], v[32:35], v[152:155], v[108:111]
	v_mfma_f32_16x16x32_bf16 v[116:119], v[20:23], v[156:159], v[116:119]
	v_mfma_f32_16x16x32_bf16 v[140:143], v[24:27], v[156:159], v[140:143]
	v_mfma_f32_16x16x32_bf16 v[144:147], v[28:31], v[156:159], v[144:147]
	v_mfma_f32_16x16x32_bf16 v[112:115], v[32:35], v[156:159], v[112:115]
	v_mfma_f32_16x16x32_bf16 v[2:5], v[20:23], v[160:163], v[2:5]
	v_mfma_f32_16x16x32_bf16 v[6:9], v[24:27], v[160:163], v[6:9]
	v_mfma_f32_16x16x32_bf16 v[12:15], v[28:31], v[160:163], v[12:15]
	v_mfma_f32_16x16x32_bf16 v[16:19], v[32:35], v[160:163], v[16:19]
	ds_read_b128 v[20:23], v10 offset:16384
	ds_read_b128 v[24:27], v10 offset:17408
	ds_read_b128 v[28:31], v10 offset:18432
	ds_read_b128 v[32:35], v10 offset:19456
	ds_read_b128 v[148:151], v0
	ds_read_b128 v[152:155], v0 offset:1024
	ds_read_b128 v[156:159], v0 offset:2048
	ds_read_b128 v[160:163], v0 offset:3072
	s_waitcnt lgkmcnt(0)
	v_mfma_f32_16x16x32_bf16 v[56:59], v[20:23], v[148:151], v[56:59]
	v_mfma_f32_16x16x32_bf16 v[60:63], v[24:27], v[148:151], v[60:63]
	v_mfma_f32_16x16x32_bf16 v[64:67], v[28:31], v[148:151], v[64:67]
	v_mfma_f32_16x16x32_bf16 v[36:39], v[32:35], v[148:151], v[36:39]
	v_mfma_f32_16x16x32_bf16 v[40:43], v[20:23], v[152:155], v[40:43]
	v_mfma_f32_16x16x32_bf16 v[68:71], v[24:27], v[152:155], v[68:71]
	v_mfma_f32_16x16x32_bf16 v[72:75], v[28:31], v[152:155], v[72:75]
	v_mfma_f32_16x16x32_bf16 v[44:47], v[32:35], v[152:155], v[44:47]
	v_mfma_f32_16x16x32_bf16 v[76:79], v[20:23], v[156:159], v[76:79]
	v_mfma_f32_16x16x32_bf16 v[80:83], v[24:27], v[156:159], v[80:83]
	v_mfma_f32_16x16x32_bf16 v[84:87], v[28:31], v[156:159], v[84:87]
	v_mfma_f32_16x16x32_bf16 v[48:51], v[32:35], v[156:159], v[48:51]
	v_mfma_f32_16x16x32_bf16 v[88:91], v[20:23], v[160:163], v[88:91]
	v_mfma_f32_16x16x32_bf16 v[92:95], v[24:27], v[160:163], v[92:95]
	v_mfma_f32_16x16x32_bf16 v[96:99], v[28:31], v[160:163], v[96:99]
	v_mfma_f32_16x16x32_bf16 v[52:55], v[32:35], v[160:163], v[52:55]
	ds_read_b128 v[148:151], v0 offset:4096
	ds_read_b128 v[152:155], v0 offset:5120
	ds_read_b128 v[156:159], v0 offset:6144
	ds_read_b128 v[160:163], v0 offset:7168
	s_waitcnt vmcnt(0) lgkmcnt(0)
	s_barrier
	v_mfma_f32_16x16x32_bf16 v[120:123], v[20:23], v[148:151], v[120:123]
	v_mfma_f32_16x16x32_bf16 v[104:107], v[20:23], v[152:155], v[104:107]
	v_mfma_f32_16x16x32_bf16 v[116:119], v[20:23], v[156:159], v[116:119]
	v_mfma_f32_16x16x32_bf16 v[20:23], v[20:23], v[160:163], v[2:5]
	s_nop 2
	v_mov_b32_e32 v4, v196
	v_mfma_f32_16x16x32_bf16 v[124:127], v[24:27], v[148:151], v[124:127]
	v_and_b32_e32 v0, 64, v4
	v_lshrrev_b32_e32 v3, 1, v4
	v_lshlrev_b32_e32 v0, 1, v0
	v_and_b32_e32 v3, 24, v3
	v_and_b32_e32 v2, 0xfffff8f, v4
	v_add3_u32 v0, 0, v0, v3
	v_mfma_f32_16x16x32_bf16 v[132:135], v[24:27], v[152:155], v[132:135]
	v_mad_u64_u32 v[2:3], s[8:9], v2, s30, v[0:1]
	v_add_u32_e32 v3, 0x1000, v2
	v_mfma_f32_16x16x32_bf16 v[140:143], v[24:27], v[156:159], v[140:143]
	v_add_u32_e32 v5, 0x6000, v2
	v_mfma_f32_16x16x32_bf16 v[6:9], v[24:27], v[160:163], v[6:9]
	v_cvt_pk_bf16_f32 v24, v60, v61
	v_cvt_pk_bf16_f32 v25, v62, v63
	v_mfma_f32_16x16x32_bf16 v[10:13], v[28:31], v[160:163], v[12:15]
	v_mfma_f32_16x16x32_bf16 v[14:17], v[32:35], v[160:163], v[16:19]
	s_nop 3
	v_cvt_pk_bf16_f32 v6, v6, v7
	v_cvt_pk_bf16_f32 v7, v8, v9
	v_cvt_pk_bf16_f32 v18, v56, v57
	v_cvt_pk_bf16_f32 v19, v58, v59
	ds_write2_b64 v2, v[18:19], v[24:25] offset1:4
	v_cvt_pk_bf16_f32 v18, v64, v65
	v_cvt_pk_bf16_f32 v19, v66, v67
	v_cvt_pk_bf16_f32 v24, v36, v37
	v_cvt_pk_bf16_f32 v25, v38, v39
	ds_write2_b64 v2, v[18:19], v[24:25] offset0:8 offset1:12
	v_cvt_pk_bf16_f32 v18, v40, v41
	v_cvt_pk_bf16_f32 v19, v42, v43
	v_cvt_pk_bf16_f32 v24, v68, v69
	v_cvt_pk_bf16_f32 v25, v70, v71
	ds_write2_b64 v3, v[18:19], v[24:25] offset0:32 offset1:36
	v_cvt_pk_bf16_f32 v18, v72, v73
	v_cvt_pk_bf16_f32 v19, v74, v75
	v_cvt_pk_bf16_f32 v24, v44, v45
	v_cvt_pk_bf16_f32 v25, v46, v47
	ds_write2_b64 v3, v[18:19], v[24:25] offset0:40 offset1:44
	v_cvt_pk_bf16_f32 v18, v76, v77
	v_cvt_pk_bf16_f32 v19, v78, v79
	v_cvt_pk_bf16_f32 v24, v80, v81
	v_cvt_pk_bf16_f32 v25, v82, v83
	v_add_u32_e32 v3, 0x2000, v2
	v_mfma_f32_16x16x32_bf16 v[128:131], v[28:31], v[148:151], v[128:131]
	ds_write2_b64 v3, v[18:19], v[24:25] offset0:64 offset1:68
	v_cvt_pk_bf16_f32 v18, v84, v85
	v_cvt_pk_bf16_f32 v19, v86, v87
	v_mfma_f32_16x16x32_bf16 v[100:103], v[32:35], v[148:151], v[100:103]
	v_cvt_pk_bf16_f32 v24, v48, v49
	v_cvt_pk_bf16_f32 v25, v50, v51
	ds_write2_b64 v3, v[18:19], v[24:25] offset0:72 offset1:76
	v_cvt_pk_bf16_f32 v18, v88, v89
	v_cvt_pk_bf16_f32 v19, v90, v91
	v_cvt_pk_bf16_f32 v24, v92, v93
	v_cvt_pk_bf16_f32 v25, v94, v95
	v_add_u32_e32 v3, 0x3000, v2
	v_mfma_f32_16x16x32_bf16 v[136:139], v[28:31], v[152:155], v[136:139]
	ds_write2_b64 v3, v[18:19], v[24:25] offset0:96 offset1:100
	v_cvt_pk_bf16_f32 v18, v96, v97
	v_cvt_pk_bf16_f32 v19, v98, v99
	v_mfma_f32_16x16x32_bf16 v[108:111], v[32:35], v[152:155], v[108:111]
	v_cvt_pk_bf16_f32 v24, v52, v53
	v_cvt_pk_bf16_f32 v25, v54, v55
	ds_write2_b64 v3, v[18:19], v[24:25] offset0:104 offset1:108
	v_cvt_pk_bf16_f32 v18, v120, v121
	v_cvt_pk_bf16_f32 v19, v122, v123
	v_cvt_pk_bf16_f32 v24, v124, v125
	v_cvt_pk_bf16_f32 v25, v126, v127
	v_add_u32_e32 v3, 0x4000, v2
	v_mfma_f32_16x16x32_bf16 v[144:147], v[28:31], v[156:159], v[144:147]
	ds_write2_b64 v3, v[18:19], v[24:25] offset0:128 offset1:132
	v_cvt_pk_bf16_f32 v18, v128, v129
	v_cvt_pk_bf16_f32 v19, v130, v131
	v_mfma_f32_16x16x32_bf16 v[112:115], v[32:35], v[156:159], v[112:115]
	v_cvt_pk_bf16_f32 v24, v100, v101
	v_cvt_pk_bf16_f32 v25, v102, v103
	ds_write2_b64 v3, v[18:19], v[24:25] offset0:136 offset1:140
	v_cvt_pk_bf16_f32 v18, v104, v105
	v_cvt_pk_bf16_f32 v19, v106, v107
	v_cvt_pk_bf16_f32 v24, v132, v133
	v_cvt_pk_bf16_f32 v25, v134, v135
	v_add_u32_e32 v3, 0x5000, v2
	ds_write2_b64 v3, v[18:19], v[24:25] offset0:160 offset1:164
	v_cvt_pk_bf16_f32 v18, v136, v137
	v_cvt_pk_bf16_f32 v19, v138, v139
	v_cvt_pk_bf16_f32 v24, v108, v109
	v_cvt_pk_bf16_f32 v25, v110, v111
	ds_write2_b64 v3, v[18:19], v[24:25] offset0:168 offset1:172
	v_cvt_pk_bf16_f32 v18, v116, v117
	v_cvt_pk_bf16_f32 v19, v118, v119
	v_cvt_pk_bf16_f32 v24, v140, v141
	v_cvt_pk_bf16_f32 v25, v142, v143
	ds_write2_b64 v5, v[18:19], v[24:25] offset0:192 offset1:196
	v_cvt_pk_bf16_f32 v2, v144, v145
	v_cvt_pk_bf16_f32 v3, v146, v147
	v_cvt_pk_bf16_f32 v18, v112, v113
	v_cvt_pk_bf16_f32 v19, v114, v115
	ds_write2_b64 v5, v[2:3], v[18:19] offset0:200 offset1:204
	v_or_b32_e32 v2, 0x70, v4
	v_mad_u64_u32 v[2:3], s[8:9], v2, s30, v[0:1]
	v_cvt_pk_bf16_f32 v18, v20, v21
	v_cvt_pk_bf16_f32 v19, v22, v23
	ds_write2_b64 v2, v[18:19], v[6:7] offset1:4
	v_cvt_pk_bf16_f32 v6, v10, v11
	v_cvt_pk_bf16_f32 v7, v12, v13
	v_cvt_pk_bf16_f32 v8, v14, v15
	v_cvt_pk_bf16_f32 v9, v16, v17
	v_lshlrev_b32_e32 v0, 4, v4
	ds_write2_b64 v2, v[6:7], v[8:9] offset0:8 offset1:12
	v_and_b32_e32 v0, 0xf0, v0
	v_ashrrev_i32_e32 v6, 4, v4
	v_lshl_add_u64 v[2:3], s[0:1], 0, v[0:1]
	v_add_u32_e32 v0, 0, v0
	v_ashrrev_i32_e32 v7, 31, v6
	v_mad_u64_u32 v[8:9], s[0:1], v6, s30, v[0:1]
	v_lshlrev_b64 v[6:7], 11, v[6:7]
	s_waitcnt lgkmcnt(0)
	s_barrier
	v_lshl_add_u64 v[10:11], v[2:3], 0, v[6:7]
	v_mov_b32_e32 v214, 0x8000
	v_mov_b32_e32 v215, 0
	ds_read_b128 v[216:219], v8
	ds_read_b128 v[228:231], v8 offset:4352
	ds_read_b128 v[232:235], v8 offset:8704
	ds_read_b128 v[236:239], v8 offset:13056
	ds_read_b128 v[240:243], v8 offset:17408
	ds_read_b128 v[244:247], v8 offset:21760
	ds_read_b128 v[248:251], v8 offset:26112
	ds_read_b128 v[252:255], v8 offset:30464
	s_waitcnt lgkmcnt(7)
	global_store_dwordx4 v[10:11], v[216:219], off
	v_lshl_add_u64 v[10:11], v[10:11], 0, v[214:215]
	s_waitcnt lgkmcnt(6)
	global_store_dwordx4 v[10:11], v[228:231], off
	v_lshl_add_u64 v[10:11], v[10:11], 0, v[214:215]
	s_waitcnt lgkmcnt(5)
	global_store_dwordx4 v[10:11], v[232:235], off
	v_lshl_add_u64 v[10:11], v[10:11], 0, v[214:215]
	s_waitcnt lgkmcnt(4)
	global_store_dwordx4 v[10:11], v[236:239], off
	v_lshl_add_u64 v[10:11], v[10:11], 0, v[214:215]
	s_waitcnt lgkmcnt(3)
	global_store_dwordx4 v[10:11], v[240:243], off
	v_lshl_add_u64 v[10:11], v[10:11], 0, v[214:215]
	s_waitcnt lgkmcnt(2)
	global_store_dwordx4 v[10:11], v[244:247], off
	v_lshl_add_u64 v[10:11], v[10:11], 0, v[214:215]
	s_waitcnt lgkmcnt(1)
	global_store_dwordx4 v[10:11], v[248:251], off
	v_lshl_add_u64 v[10:11], v[10:11], 0, v[214:215]
	s_waitcnt lgkmcnt(0)
	global_store_dwordx4 v[10:11], v[252:255], off
	v_lshl_add_u64 v[10:11], v[10:11], 0, v[214:215]
	ds_read_b128 v[216:219], v8 offset:34816
	ds_read_b128 v[228:231], v8 offset:39168
	ds_read_b128 v[232:235], v8 offset:43520
	ds_read_b128 v[236:239], v8 offset:47872
	ds_read_b128 v[240:243], v8 offset:52224
	ds_read_b128 v[244:247], v8 offset:56576
	ds_read_b128 v[248:251], v8 offset:60928
	ds_read_b128 v[252:255], v8 offset:65280
	s_waitcnt lgkmcnt(7)
	global_store_dwordx4 v[10:11], v[216:219], off
	v_lshl_add_u64 v[10:11], v[10:11], 0, v[214:215]
	s_waitcnt lgkmcnt(6)
	global_store_dwordx4 v[10:11], v[228:231], off
	v_lshl_add_u64 v[10:11], v[10:11], 0, v[214:215]
	s_waitcnt lgkmcnt(5)
	global_store_dwordx4 v[10:11], v[232:235], off
	v_lshl_add_u64 v[10:11], v[10:11], 0, v[214:215]
	s_waitcnt lgkmcnt(4)
	global_store_dwordx4 v[10:11], v[236:239], off
	v_lshl_add_u64 v[10:11], v[10:11], 0, v[214:215]
	s_waitcnt lgkmcnt(3)
	global_store_dwordx4 v[10:11], v[240:243], off
	v_lshl_add_u64 v[10:11], v[10:11], 0, v[214:215]
	s_waitcnt lgkmcnt(2)
	global_store_dwordx4 v[10:11], v[244:247], off
	v_lshl_add_u64 v[10:11], v[10:11], 0, v[214:215]
	s_waitcnt lgkmcnt(1)
	global_store_dwordx4 v[10:11], v[248:251], off
	v_lshl_add_u64 v[10:11], v[10:11], 0, v[214:215]
	s_waitcnt lgkmcnt(0)
	global_store_dwordx4 v[10:11], v[252:255], off
	s_barrier
	s_branch .LBB0_198
